# gate int8 epilogue: the 4 late row-stat loads join the first load batch (one round trip); out-proj and FFN-down epilogues: row-max partials prefetched by LDS-DMA in the last K-iteration
# speedup vs baseline: 1.0108x; 1.0007x over previous
.LBB0_1029:
	v_mov_b32_e32 v156, v0
	s_lshl_b32 s10, s68, 10
	s_lshl_b32 s5, s70, 8
	v_lshrrev_b32_e32 v130, 1, v156
	s_ashr_i32 s11, s10, 31
	s_ashr_i32 s4, s68, 1
	v_and_or_b32 v130, v130, 24, s5
	s_lshl_b64 s[10:11], s[10:11], 2
	v_or_b32_e32 v130, s63, v130
	s_add_u32 s10, s57, s10
	s_addc_u32 s11, s60, s11
	v_ashrrev_i32_e32 v131, 31, v130
	v_lshl_add_u64 v[138:139], v[130:131], 2, s[10:11]
	global_load_dwordx4 v[130:133], v[138:139], off offset:16
	global_load_dwordx4 v[134:137], v[138:139], off
	global_load_dwordx4 v[160:163], v[138:139], off offset:528
	s_nop 0
	global_load_dwordx4 v[138:141], v[138:139], off offset:512
	v_and_b32_e32 v152, 15, v156
	s_lshl_b32 s10, s67, 8
	v_or_b32_e32 v142, s62, v152
	v_add_u32_e32 v142, s10, v142
	v_ashrrev_i32_e32 v143, 31, v142
	s_ashr_i32 s5, s4, 31
	v_lshl_add_u64 v[144:145], v[142:143], 2, s[22:23]
	v_add_u32_e32 v146, 0x80, v142
	v_add_u32_e32 v148, 0x90, v142
	v_add_u32_e32 v150, 0xa0, v142
	v_add_u32_e32 v142, 0xb0, v142
	s_lshl_b64 s[4:5], s[4:5], 2
	v_ashrrev_i32_e32 v143, 31, v142
	s_add_u32 s4, s12, s4
	v_ashrrev_i32_e32 v147, 31, v146
	v_ashrrev_i32_e32 v149, 31, v148
	v_ashrrev_i32_e32 v151, 31, v150
	v_lshl_add_u64 v[142:143], v[142:143], 2, s[22:23]
	s_addc_u32 s5, s61, s5
	s_add_i32 s10, s10, s62
	v_lshl_add_u64 v[146:147], v[146:147], 2, s[22:23]
	v_lshl_add_u64 v[148:149], v[148:149], 2, s[22:23]
	v_lshl_add_u64 v[150:151], v[150:151], 2, s[22:23]
	global_load_dword v157, v[144:145], off
	global_load_dword v205, v[144:145], off offset:64
	global_load_dword v207, v[144:145], off offset:128
	global_load_dword v242, v[144:145], off offset:192
	global_load_dword v243, v[146:147], off
	global_load_dword v244, v[148:149], off
	global_load_dword v245, v[150:151], off
	global_load_dword v155, v[142:143], off
	v_or_b32_e32 v142, s10, v152
	v_ashrrev_i32_e32 v143, 31, v142
	v_lshlrev_b64 v[144:145], 5, v[142:143]
	v_lshl_add_u64 v[176:177], s[20:21], 0, v[144:145]
	global_load_dword v154, v203, s[4:5] sc1
	global_load_dwordx4 v[164:167], v[176:177], off
	global_load_dwordx4 v[168:171], v[176:177], off offset:16
	v_or_b32_e32 v144, 16, v142
	v_ashrrev_i32_e32 v145, 31, v144
	v_lshlrev_b64 v[144:145], 5, v[144:145]
	v_lshl_add_u64 v[144:145], s[20:21], 0, v[144:145]
	global_load_dwordx4 v[172:175], v[144:145], off
	global_load_dwordx4 v[180:183], v[144:145], off offset:16
	v_or_b32_e32 v144, 32, v142
	v_ashrrev_i32_e32 v145, 31, v144
	v_lshlrev_b64 v[144:145], 5, v[144:145]
	v_lshl_add_u64 v[144:145], s[20:21], 0, v[144:145]
	global_load_dwordx4 v[184:187], v[144:145], off
	global_load_dwordx4 v[188:191], v[144:145], off offset:16
	v_or_b32_e32 v142, 48, v142
	v_ashrrev_i32_e32 v143, 31, v142
	v_lshlrev_b64 v[142:143], 5, v[142:143]
	v_lshl_add_u64 v[142:143], s[20:21], 0, v[142:143]
	global_load_dwordx4 v[192:195], v[142:143], off
	global_load_dwordx4 v[196:199], v[142:143], off offset:16
	s_mov_b64 s[4:5], 0x1000
	v_lshl_add_u64 v[142:143], v[176:177], 0, s[4:5]
	s_movk_i32 s4, 0x1000
	v_add_co_u32_e32 v200, vcc, s4, v176
	s_mov_b32 s4, 0xc0ffd1be
	s_nop 0
	v_addc_co_u32_e32 v201, vcc, 0, v177, vcc
	global_load_dwordx4 v[208:211], v[200:201], off
	global_load_dwordx4 v[212:215], v[142:143], off offset:16
	v_mov_b64_e32 v[240:241], s[4:5]
	s_mov_b64 s[4:5], 0x1200
	s_mov_b32 s10, 0x3fb8aa3b
	v_lshl_add_u64 v[142:143], v[176:177], 0, s[4:5]
	global_load_dwordx4 v[216:219], v[200:201], off offset:512
	global_load_dwordx4 v[220:223], v[142:143], off offset:16
	global_load_dwordx4 v[224:227], v[200:201], off offset:1024
	global_load_dwordx4 v[236:239], v[200:201], off offset:1040
	global_load_dwordx4 v[250:253], v[200:201], off offset:1536
	global_load_dwordx2 v[246:247], v[200:201], off offset:1552
	global_load_dwordx2 v[254:255], v[200:201], off offset:1560
	s_mov_b64 s[4:5], 0x1400
	v_cvt_f32_i32_e32 v129, v129
	v_cvt_f32_i32_e32 v128, v128
	v_cvt_f32_i32_e32 v127, v127
	v_cvt_f32_i32_e32 v126, v126
	v_cvt_f32_i32_e32 v121, v121
	v_cvt_f32_i32_e32 v120, v120
	v_cvt_f32_i32_e32 v119, v119
	v_cvt_f32_i32_e32 v118, v118
	v_cvt_f32_i32_e32 v117, v117
	v_cvt_f32_i32_e32 v116, v116
	v_cvt_f32_i32_e32 v115, v115
	v_cvt_f32_i32_e32 v114, v114
	v_cvt_f32_i32_e32 v105, v105
	v_cvt_f32_i32_e32 v104, v104
	v_cvt_f32_i32_e32 v103, v103
	v_cvt_f32_i32_e32 v102, v102
	s_waitcnt vmcnt(0)
	v_xor_b32_e32 v133, 0x80000000, v133
	v_xor_b32_e32 v132, 0x80000000, v132
	v_pk_fma_f32 v[146:147], v[130:131], s[10:11], v[240:241] op_sel_hi:[1,0,0] neg_lo:[1,0,0] neg_hi:[1,0,0]
	v_xor_b32_e32 v131, 0x80000000, v141
	v_xor_b32_e32 v130, 0x80000000, v140
	v_pk_fma_f32 v[148:149], v[132:133], s[10:11], v[240:241] op_sel_hi:[1,0,0]
	v_pk_fma_f32 v[144:145], v[130:131], s[10:11], v[240:241] op_sel_hi:[1,0,0]
	v_xor_b32_e32 v131, 0x80000000, v163
	v_xor_b32_e32 v130, 0x80000000, v162
	s_mov_b64 s[4:5], 0x1600
	v_xor_b32_e32 v137, 0x80000000, v137
	v_xor_b32_e32 v136, 0x80000000, v136
	v_pk_fma_f32 v[142:143], v[138:139], s[10:11], v[240:241] op_sel_hi:[1,0,0] neg_lo:[1,0,0] neg_hi:[1,0,0]
	v_pk_fma_f32 v[138:139], v[130:131], s[10:11], v[240:241] op_sel_hi:[1,0,0]
	v_pk_fma_f32 v[150:151], v[134:135], s[10:11], v[240:241] op_sel_hi:[1,0,0] neg_lo:[1,0,0] neg_hi:[1,0,0]
	v_pk_fma_f32 v[152:153], v[136:137], s[10:11], v[240:241] op_sel_hi:[1,0,0]
	v_pk_fma_f32 v[140:141], v[160:161], s[10:11], v[240:241] op_sel_hi:[1,0,0] neg_lo:[1,0,0] neg_hi:[1,0,0]
	v_cvt_f32_i32_e32 v101, v101
	v_cvt_f32_i32_e32 v100, v100
	v_cvt_f32_i32_e32 v99, v99
	v_cvt_f32_i32_e32 v98, v98
	v_cvt_f32_i32_e32 v89, v89
	v_cvt_f32_i32_e32 v88, v88
	v_cvt_f32_i32_e32 v87, v87
	v_cvt_f32_i32_e32 v86, v86
	v_cvt_f32_i32_e32 v85, v85
	v_cvt_f32_i32_e32 v84, v84
	v_cvt_f32_i32_e32 v83, v83
	v_mov_b32_e32 v160, v164
	v_mov_b32_e32 v161, v168
	v_mov_b32_e32 v168, v165
	v_mov_b32_e32 v162, v166
	v_mov_b32_e32 v163, v170
	v_mov_b32_e32 v170, v167
	v_pk_add_f32 v[160:161], v[160:161], v[168:169]
	v_pk_add_f32 v[162:163], v[162:163], v[170:171]
	v_cvt_f32_i32_e32 v167, v111
	v_pk_add_f32 v[160:161], v[160:161], v[162:163]
	v_mov_b32_e32 v162, v174
	v_add_f32_e32 v160, v160, v161
	v_fmamk_f32 v160, v160, 0x3a000000, v1
	v_rsq_f32_e32 v164, v160
	v_mov_b32_e32 v160, v172
	v_mov_b32_e32 v161, v180
	v_mov_b32_e32 v180, v173
	v_mov_b32_e32 v163, v182
	v_mov_b32_e32 v182, v175
	v_pk_add_f32 v[160:161], v[160:161], v[180:181]
	v_pk_add_f32 v[162:163], v[162:163], v[182:183]
	v_cvt_f32_i32_e32 v166, v110
	v_pk_add_f32 v[160:161], v[160:161], v[162:163]
	v_mov_b32_e32 v162, v186
	v_add_f32_e32 v160, v160, v161
	v_fmamk_f32 v160, v160, 0x3a000000, v1
	v_rsq_f32_e32 v172, v160
	v_mov_b32_e32 v160, v184
	v_mov_b32_e32 v161, v188
	v_mov_b32_e32 v188, v185
	v_mov_b32_e32 v163, v190
	v_mov_b32_e32 v190, v187
	v_pk_add_f32 v[160:161], v[160:161], v[188:189]
	v_pk_add_f32 v[162:163], v[162:163], v[190:191]
	v_cvt_f32_i32_e32 v169, v109
	v_pk_add_f32 v[160:161], v[160:161], v[162:163]
	v_mov_b32_e32 v162, v194
	v_add_f32_e32 v160, v160, v161
	v_fmamk_f32 v160, v160, 0x3a000000, v1
	v_rsq_f32_e32 v173, v160
	v_mov_b32_e32 v160, v192
	v_mov_b32_e32 v161, v196
	v_mov_b32_e32 v196, v193
	v_mov_b32_e32 v163, v198
	v_mov_b32_e32 v198, v195
	v_pk_add_f32 v[160:161], v[160:161], v[196:197]
	v_pk_add_f32 v[162:163], v[162:163], v[198:199]
	v_cvt_f32_i32_e32 v168, v108
	v_pk_add_f32 v[160:161], v[160:161], v[162:163]
	v_mov_b32_e32 v162, v210
	v_add_f32_e32 v160, v160, v161
	v_fmamk_f32 v160, v160, 0x3a000000, v1
	v_rsq_f32_e32 v174, v160
	v_mov_b32_e32 v160, v208
	v_mov_b32_e32 v161, v212
	v_mov_b32_e32 v212, v209
	v_mov_b32_e32 v163, v214
	v_mov_b32_e32 v214, v211
	v_pk_add_f32 v[160:161], v[160:161], v[212:213]
	v_pk_add_f32 v[162:163], v[162:163], v[214:215]
	v_cvt_f32_i32_e32 v111, v95
	v_pk_add_f32 v[160:161], v[160:161], v[162:163]
	v_mov_b32_e32 v162, v218
	v_add_f32_e32 v160, v160, v161
	v_fmamk_f32 v160, v160, 0x3a000000, v1
	v_rsq_f32_e32 v175, v160
	v_mov_b32_e32 v160, v216
	v_mov_b32_e32 v161, v220
	v_mov_b32_e32 v220, v217
	v_mov_b32_e32 v163, v222
	v_mov_b32_e32 v222, v219
	v_pk_add_f32 v[160:161], v[160:161], v[220:221]
	v_pk_add_f32 v[162:163], v[162:163], v[222:223]
	v_cvt_f32_i32_e32 v110, v94
	v_pk_add_f32 v[160:161], v[160:161], v[162:163]
	v_cvt_f32_i32_e32 v109, v93
	v_add_f32_e32 v160, v160, v161
	v_cvt_f32_i32_e32 v108, v92
	v_cvt_f32_i32_e32 v95, v79
	v_cvt_f32_i32_e32 v94, v78
	v_cvt_f32_i32_e32 v93, v77
	v_cvt_f32_i32_e32 v92, v76
	v_cvt_f32_i32_e32 v79, v71
	v_cvt_f32_i32_e32 v78, v70
	v_cvt_f32_i32_e32 v77, v69
	v_cvt_f32_i32_e32 v76, v68
	v_cvt_f32_i32_e32 v71, v63
	v_cvt_f32_i32_e32 v70, v62
	v_cvt_f32_i32_e32 v69, v61
	v_cvt_f32_i32_e32 v68, v60
	v_cvt_f32_i32_e32 v63, v47
	v_cvt_f32_i32_e32 v62, v46
	v_cvt_f32_i32_e32 v61, v45
	v_cvt_f32_i32_e32 v60, v44
	v_cvt_f32_i32_e32 v47, v31
	v_cvt_f32_i32_e32 v46, v30
	v_cvt_f32_i32_e32 v45, v29
	v_cvt_f32_i32_e32 v44, v28
	v_cvt_f32_i32_e32 v31, v37
	v_cvt_f32_i32_e32 v30, v36
	v_cvt_f32_i32_e32 v29, v35
	v_cvt_f32_i32_e32 v28, v34
	v_mov_b32_e32 v34, v250
	v_mov_b32_e32 v35, v246
	v_mov_b32_e32 v130, v251
	v_mov_b32_e32 v131, v247
	v_mov_b32_e32 v36, v252
	v_mov_b32_e32 v37, v254
	v_mov_b32_e32 v132, v253
	v_mov_b32_e32 v133, v255
	v_fmamk_f32 v160, v160, 0x3a000000, v1
	v_pk_add_f32 v[34:35], v[34:35], v[130:131]
	v_pk_add_f32 v[36:37], v[36:37], v[132:133]
	v_rsq_f32_e32 v176, v160
	v_mov_b32_e32 v160, v224
	v_mov_b32_e32 v161, v236
	v_mov_b32_e32 v236, v225
	v_mov_b32_e32 v162, v226
	v_mov_b32_e32 v163, v238
	v_mov_b32_e32 v238, v227
	v_pk_add_f32 v[34:35], v[34:35], v[36:37]
	v_pk_add_f32 v[160:161], v[160:161], v[236:237]
	v_pk_add_f32 v[162:163], v[162:163], v[238:239]
	v_cvt_f32_i32_e32 v171, v107
	v_cvt_f32_i32_e32 v107, v91
	v_cvt_f32_i32_e32 v91, v75
	v_cvt_f32_i32_e32 v75, v67
	v_cvt_f32_i32_e32 v67, v59
	v_cvt_f32_i32_e32 v59, v43
	v_cvt_f32_i32_e32 v43, v27
	v_cvt_f32_i32_e32 v27, v25
	v_cvt_f32_i32_e32 v25, v23
	v_add_f32_e32 v23, v34, v35
	v_pk_add_f32 v[160:161], v[160:161], v[162:163]
	v_fmamk_f32 v23, v23, 0x3a000000, v1
	v_add_f32_e32 v160, v160, v161
	v_cvt_f32_i32_e32 v161, v125
	v_mul_f32_e32 v125, v205, v172
	v_rsq_f32_e32 v205, v23
	v_mul_f32_e32 v157, v157, v164
	v_cvt_f32_i32_e32 v170, v106
	v_cvt_f32_i32_e32 v106, v90
	v_cvt_f32_i32_e32 v90, v74
	v_cvt_f32_i32_e32 v74, v66
	v_cvt_f32_i32_e32 v66, v58
	v_cvt_f32_i32_e32 v58, v42
	v_cvt_f32_i32_e32 v42, v26
	v_cvt_f32_i32_e32 v26, v24
	v_cvt_f32_i32_e32 v24, v22
	v_cvt_f32_i32_e32 v23, v21
	v_cvt_f32_i32_e32 v22, v20
	v_pk_mul_f32 v[20:21], v[154:155], v[204:205]
	v_cvt_f32_i32_e32 v165, v113
	v_mul_f32_e32 v34, v20, v157
	v_pk_fma_f32 v[36:37], v[34:35], v[128:129], v[152:153] op_sel_hi:[0,1,1]
	v_exp_f32_e32 v35, v37
	v_cvt_f32_i32_e32 v164, v112
	v_cvt_f32_i32_e32 v113, v97
	v_cvt_f32_i32_e32 v112, v96
	v_cvt_f32_i32_e32 v97, v81
	v_cvt_f32_i32_e32 v96, v80
	v_cvt_f32_i32_e32 v81, v73
	v_cvt_f32_i32_e32 v80, v72
	v_cvt_f32_i32_e32 v73, v65
	v_cvt_f32_i32_e32 v72, v64
	v_cvt_f32_i32_e32 v65, v49
	v_cvt_f32_i32_e32 v64, v48
	v_cvt_f32_i32_e32 v49, v33
	v_cvt_f32_i32_e32 v48, v32
	v_cvt_f32_i32_e32 v33, v39
	v_cvt_f32_i32_e32 v32, v38
	v_pk_fma_f32 v[38:39], v[34:35], v[126:127], v[150:151] op_sel_hi:[0,1,1]
	v_exp_f32_e32 v38, v38
	v_exp_f32_e32 v37, v39
	v_exp_f32_e32 v36, v36
	v_fmamk_f32 v160, v160, 0x3a000000, v1
	v_add_f32_e32 v38, 0x3b808081, v38
	v_add_f32_e32 v35, 0x3b808081, v35
	v_add_f32_e32 v37, 0x3b808081, v37
	v_rcp_f32_e32 v38, v38
	v_rsq_f32_e32 v177, v160
	v_cvt_f32_i32_e32 v160, v124
	v_rcp_f32_e32 v35, v35
	v_rcp_f32_e32 v37, v37
	v_add_f32_e32 v36, 0x3b808081, v36
	v_rcp_f32_e32 v39, v36
	v_cvt_f32_i32_e32 v163, v123
	v_cvt_f32_i32_e32 v162, v122
	v_cvt_pk_u8_f32 v36, v38, 0, 0
	v_cvt_pk_u8_f32 v38, v37, 1, v36
	v_pk_fma_f32 v[36:37], v[34:35], v[160:161], v[148:149] op_sel_hi:[0,1,1]
	v_exp_f32_e32 v37, v37
	v_cvt_pk_u8_f32 v38, v39, 2, v38
	v_cvt_pk_u8_f32 v180, v35, 3, v38
	v_pk_fma_f32 v[38:39], v[34:35], v[162:163], v[146:147] op_sel_hi:[0,1,1]
	v_exp_f32_e32 v38, v38
	v_add_f32_e32 v35, 0x3b808081, v37
	v_exp_f32_e32 v37, v39
	v_exp_f32_e32 v36, v36
	v_add_f32_e32 v38, 0x3b808081, v38
	v_rcp_f32_e32 v38, v38
	v_add_f32_e32 v37, 0x3b808081, v37
	v_rcp_f32_e32 v35, v35
	v_rcp_f32_e32 v37, v37
	v_add_f32_e32 v36, 0x3b808081, v36
	v_rcp_f32_e32 v39, v36
	v_cvt_pk_u8_f32 v36, v38, 0, 0
	v_cvt_pk_u8_f32 v38, v37, 1, v36
	v_pk_fma_f32 v[36:37], v[34:35], v[164:165], v[144:145] op_sel_hi:[0,1,1]
	v_exp_f32_e32 v37, v37
	v_cvt_pk_u8_f32 v38, v39, 2, v38
	v_cvt_pk_u8_f32 v181, v35, 3, v38
	v_pk_fma_f32 v[38:39], v[34:35], v[166:167], v[142:143] op_sel_hi:[0,1,1]
	v_exp_f32_e32 v38, v38
	v_add_f32_e32 v35, 0x3b808081, v37
	v_exp_f32_e32 v37, v39
	v_exp_f32_e32 v36, v36
	v_add_f32_e32 v38, 0x3b808081, v38
	v_rcp_f32_e32 v38, v38
	v_add_f32_e32 v37, 0x3b808081, v37
	v_rcp_f32_e32 v37, v37
	v_add_f32_e32 v36, 0x3b808081, v36
	v_rcp_f32_e32 v39, v36
	v_rcp_f32_e32 v35, v35
	v_cvt_pk_u8_f32 v36, v38, 0, 0
	v_cvt_pk_u8_f32 v38, v37, 1, v36
	v_cvt_pk_u8_f32 v38, v39, 2, v38
	v_pk_fma_f32 v[36:37], v[34:35], v[168:169], v[138:139] op_sel_hi:[0,1,1]
	v_cvt_pk_u8_f32 v182, v35, 3, v38
	v_pk_fma_f32 v[34:35], v[34:35], v[170:171], v[140:141] op_sel_hi:[0,1,1]
	v_exp_f32_e32 v34, v34
	v_exp_f32_e32 v35, v35
	v_exp_f32_e32 v36, v36
	v_exp_f32_e32 v37, v37
	v_add_f32_e32 v34, 0x3b808081, v34
	v_add_f32_e32 v35, 0x3b808081, v35
	v_rcp_f32_e32 v34, v34
	v_rcp_f32_e32 v35, v35
	v_add_f32_e32 v36, 0x3b808081, v36
	v_add_f32_e32 v37, 0x3b808081, v37
	v_rcp_f32_e32 v39, v36
	v_cvt_pk_u8_f32 v34, v34, 0, 0
	v_rcp_f32_e32 v38, v37
	v_cvt_pk_u8_f32 v35, v35, 1, v34
	v_mul_f32_e32 v34, v20, v125
	v_pk_fma_f32 v[36:37], v[34:35], v[120:121], v[152:153] op_sel_hi:[0,1,1]
	v_exp_f32_e32 v37, v37
	v_cvt_pk_u8_f32 v35, v39, 2, v35
	v_cvt_pk_u8_f32 v183, v38, 3, v35
	v_pk_fma_f32 v[38:39], v[34:35], v[118:119], v[150:151] op_sel_hi:[0,1,1]
	v_exp_f32_e32 v38, v38
	v_add_f32_e32 v35, 0x3b808081, v37
	v_exp_f32_e32 v37, v39
	v_exp_f32_e32 v36, v36
	v_add_f32_e32 v38, 0x3b808081, v38
	v_rcp_f32_e32 v38, v38
	v_add_f32_e32 v37, 0x3b808081, v37
	v_rcp_f32_e32 v35, v35
	v_rcp_f32_e32 v37, v37
	v_add_f32_e32 v36, 0x3b808081, v36
	v_rcp_f32_e32 v39, v36
	v_cvt_pk_u8_f32 v36, v38, 0, 0
	v_cvt_pk_u8_f32 v38, v37, 1, v36
	v_pk_fma_f32 v[36:37], v[34:35], v[116:117], v[148:149] op_sel_hi:[0,1,1]
	v_exp_f32_e32 v37, v37
	v_cvt_pk_u8_f32 v38, v39, 2, v38
	v_cvt_pk_u8_f32 v184, v35, 3, v38
	v_pk_fma_f32 v[38:39], v[34:35], v[114:115], v[146:147] op_sel_hi:[0,1,1]
	v_exp_f32_e32 v38, v38
	v_add_f32_e32 v35, 0x3b808081, v37
	v_exp_f32_e32 v37, v39
	v_exp_f32_e32 v36, v36
	v_add_f32_e32 v38, 0x3b808081, v38
	v_rcp_f32_e32 v38, v38
	v_add_f32_e32 v37, 0x3b808081, v37
	v_rcp_f32_e32 v35, v35
	v_rcp_f32_e32 v37, v37
	v_add_f32_e32 v36, 0x3b808081, v36
	v_rcp_f32_e32 v39, v36
	v_cvt_pk_u8_f32 v36, v38, 0, 0
	v_cvt_pk_u8_f32 v38, v37, 1, v36
	v_pk_fma_f32 v[36:37], v[34:35], v[112:113], v[144:145] op_sel_hi:[0,1,1]
	v_exp_f32_e32 v37, v37
	v_cvt_pk_u8_f32 v38, v39, 2, v38
	v_cvt_pk_u8_f32 v185, v35, 3, v38
	v_pk_fma_f32 v[38:39], v[34:35], v[110:111], v[142:143] op_sel_hi:[0,1,1]
	v_exp_f32_e32 v38, v38
	v_add_f32_e32 v35, 0x3b808081, v37
	v_exp_f32_e32 v37, v39
	v_exp_f32_e32 v36, v36
	v_add_f32_e32 v38, 0x3b808081, v38
	v_rcp_f32_e32 v38, v38
	v_add_f32_e32 v37, 0x3b808081, v37
	v_rcp_f32_e32 v37, v37
	v_add_f32_e32 v36, 0x3b808081, v36
	v_rcp_f32_e32 v39, v36
	v_rcp_f32_e32 v35, v35
	v_cvt_pk_u8_f32 v36, v38, 0, 0
	v_cvt_pk_u8_f32 v38, v37, 1, v36
	v_cvt_pk_u8_f32 v38, v39, 2, v38
	v_pk_fma_f32 v[36:37], v[34:35], v[108:109], v[138:139] op_sel_hi:[0,1,1]
	v_cvt_pk_u8_f32 v186, v35, 3, v38
	v_pk_fma_f32 v[34:35], v[34:35], v[106:107], v[140:141] op_sel_hi:[0,1,1]
	v_exp_f32_e32 v34, v34
	v_exp_f32_e32 v35, v35
	v_exp_f32_e32 v36, v36
	v_exp_f32_e32 v37, v37
	v_add_f32_e32 v34, 0x3b808081, v34
	v_add_f32_e32 v35, 0x3b808081, v35
	v_rcp_f32_e32 v34, v34
	v_rcp_f32_e32 v35, v35
	v_add_f32_e32 v36, 0x3b808081, v36
	v_mul_f32_e32 v172, v207, v173
	v_add_f32_e32 v37, 0x3b808081, v37
	v_rcp_f32_e32 v39, v36
	v_cvt_pk_u8_f32 v34, v34, 0, 0
	v_rcp_f32_e32 v38, v37
	v_cvt_pk_u8_f32 v35, v35, 1, v34
	v_mul_f32_e32 v34, v20, v172
	v_pk_fma_f32 v[36:37], v[34:35], v[104:105], v[152:153] op_sel_hi:[0,1,1]
	v_exp_f32_e32 v37, v37
	v_cvt_pk_u8_f32 v35, v39, 2, v35
	v_cvt_pk_u8_f32 v187, v38, 3, v35
	v_pk_fma_f32 v[38:39], v[34:35], v[102:103], v[150:151] op_sel_hi:[0,1,1]
	v_exp_f32_e32 v38, v38
	v_add_f32_e32 v35, 0x3b808081, v37
	v_exp_f32_e32 v37, v39
	v_exp_f32_e32 v36, v36
	v_add_f32_e32 v38, 0x3b808081, v38
	v_rcp_f32_e32 v38, v38
	v_add_f32_e32 v37, 0x3b808081, v37
	v_rcp_f32_e32 v35, v35
	v_rcp_f32_e32 v37, v37
	v_add_f32_e32 v36, 0x3b808081, v36
	v_rcp_f32_e32 v39, v36
	v_cvt_pk_u8_f32 v36, v38, 0, 0
	v_cvt_pk_u8_f32 v38, v37, 1, v36
	v_pk_fma_f32 v[36:37], v[34:35], v[100:101], v[148:149] op_sel_hi:[0,1,1]
	v_exp_f32_e32 v37, v37
	v_cvt_pk_u8_f32 v38, v39, 2, v38
	v_cvt_pk_u8_f32 v188, v35, 3, v38
	v_pk_fma_f32 v[38:39], v[34:35], v[98:99], v[146:147] op_sel_hi:[0,1,1]
	v_exp_f32_e32 v38, v38
	v_add_f32_e32 v35, 0x3b808081, v37
	v_exp_f32_e32 v37, v39
	v_exp_f32_e32 v36, v36
	v_add_f32_e32 v38, 0x3b808081, v38
	v_rcp_f32_e32 v38, v38
	v_add_f32_e32 v37, 0x3b808081, v37
	v_rcp_f32_e32 v35, v35
	v_rcp_f32_e32 v37, v37
	v_add_f32_e32 v36, 0x3b808081, v36
	v_rcp_f32_e32 v39, v36
	v_cvt_pk_u8_f32 v36, v38, 0, 0
	v_cvt_pk_u8_f32 v38, v37, 1, v36
	v_pk_fma_f32 v[36:37], v[34:35], v[96:97], v[144:145] op_sel_hi:[0,1,1]
	v_exp_f32_e32 v37, v37
	v_cvt_pk_u8_f32 v38, v39, 2, v38
	v_cvt_pk_u8_f32 v189, v35, 3, v38
	v_pk_fma_f32 v[38:39], v[34:35], v[94:95], v[142:143] op_sel_hi:[0,1,1]
	v_exp_f32_e32 v38, v38
	v_add_f32_e32 v35, 0x3b808081, v37
	v_exp_f32_e32 v37, v39
	v_exp_f32_e32 v36, v36
	v_add_f32_e32 v38, 0x3b808081, v38
	v_rcp_f32_e32 v38, v38
	v_add_f32_e32 v37, 0x3b808081, v37
	v_rcp_f32_e32 v37, v37
	v_add_f32_e32 v36, 0x3b808081, v36
	v_rcp_f32_e32 v39, v36
	v_rcp_f32_e32 v35, v35
	v_cvt_pk_u8_f32 v36, v38, 0, 0
	v_cvt_pk_u8_f32 v38, v37, 1, v36
	v_cvt_pk_u8_f32 v38, v39, 2, v38
	v_pk_fma_f32 v[36:37], v[34:35], v[92:93], v[138:139] op_sel_hi:[0,1,1]
	v_cvt_pk_u8_f32 v190, v35, 3, v38
	v_pk_fma_f32 v[34:35], v[34:35], v[90:91], v[140:141] op_sel_hi:[0,1,1]
	v_exp_f32_e32 v34, v34
	v_exp_f32_e32 v35, v35
	v_exp_f32_e32 v36, v36
	v_exp_f32_e32 v37, v37
	v_add_f32_e32 v34, 0x3b808081, v34
	v_add_f32_e32 v35, 0x3b808081, v35
	v_rcp_f32_e32 v34, v34
	v_rcp_f32_e32 v35, v35
	v_add_f32_e32 v36, 0x3b808081, v36
	v_mul_f32_e32 v173, v242, v174
	v_add_f32_e32 v37, 0x3b808081, v37
	v_rcp_f32_e32 v39, v36
	v_cvt_pk_u8_f32 v34, v34, 0, 0
	v_rcp_f32_e32 v38, v37
	v_cvt_pk_u8_f32 v35, v35, 1, v34
	v_mul_f32_e32 v34, v20, v173
	v_pk_fma_f32 v[36:37], v[34:35], v[88:89], v[152:153] op_sel_hi:[0,1,1]
	v_exp_f32_e32 v37, v37
	v_cvt_pk_u8_f32 v35, v39, 2, v35
	v_cvt_pk_u8_f32 v191, v38, 3, v35
	v_pk_fma_f32 v[38:39], v[34:35], v[86:87], v[150:151] op_sel_hi:[0,1,1]
	v_exp_f32_e32 v38, v38
	v_add_f32_e32 v35, 0x3b808081, v37
	v_exp_f32_e32 v37, v39
	v_exp_f32_e32 v36, v36
	v_add_f32_e32 v38, 0x3b808081, v38
	v_rcp_f32_e32 v38, v38
	v_add_f32_e32 v37, 0x3b808081, v37
	v_rcp_f32_e32 v35, v35
	v_rcp_f32_e32 v37, v37
	v_add_f32_e32 v36, 0x3b808081, v36
	v_rcp_f32_e32 v39, v36
	v_cvt_f32_i32_e32 v82, v82
	v_cvt_pk_u8_f32 v36, v38, 0, 0
	v_cvt_pk_u8_f32 v38, v37, 1, v36
	v_pk_fma_f32 v[36:37], v[34:35], v[84:85], v[148:149] op_sel_hi:[0,1,1]
	v_exp_f32_e32 v37, v37
	v_cvt_pk_u8_f32 v38, v39, 2, v38
	v_cvt_pk_u8_f32 v192, v35, 3, v38
	v_pk_fma_f32 v[38:39], v[34:35], v[82:83], v[146:147] op_sel_hi:[0,1,1]
	v_exp_f32_e32 v38, v38
	v_add_f32_e32 v35, 0x3b808081, v37
	v_exp_f32_e32 v37, v39
	v_exp_f32_e32 v36, v36
	v_add_f32_e32 v38, 0x3b808081, v38
	v_rcp_f32_e32 v38, v38
	v_add_f32_e32 v37, 0x3b808081, v37
	v_rcp_f32_e32 v35, v35
	v_rcp_f32_e32 v37, v37
	v_add_f32_e32 v36, 0x3b808081, v36
	v_rcp_f32_e32 v39, v36
	v_cvt_pk_u8_f32 v36, v38, 0, 0
	v_cvt_pk_u8_f32 v38, v37, 1, v36
	v_pk_fma_f32 v[36:37], v[34:35], v[80:81], v[144:145] op_sel_hi:[0,1,1]
	v_exp_f32_e32 v37, v37
	v_cvt_pk_u8_f32 v38, v39, 2, v38
	v_cvt_pk_u8_f32 v193, v35, 3, v38
	v_pk_fma_f32 v[38:39], v[34:35], v[78:79], v[142:143] op_sel_hi:[0,1,1]
	v_exp_f32_e32 v38, v38
	v_add_f32_e32 v35, 0x3b808081, v37
	v_exp_f32_e32 v37, v39
	v_exp_f32_e32 v36, v36
	v_add_f32_e32 v38, 0x3b808081, v38
	v_rcp_f32_e32 v38, v38
	v_add_f32_e32 v37, 0x3b808081, v37
	v_rcp_f32_e32 v37, v37
	v_add_f32_e32 v36, 0x3b808081, v36
	v_rcp_f32_e32 v39, v36
	v_rcp_f32_e32 v35, v35
	v_cvt_pk_u8_f32 v36, v38, 0, 0
	v_cvt_pk_u8_f32 v38, v37, 1, v36
	v_cvt_pk_u8_f32 v38, v39, 2, v38
	v_pk_fma_f32 v[36:37], v[34:35], v[76:77], v[138:139] op_sel_hi:[0,1,1]
	v_cvt_pk_u8_f32 v194, v35, 3, v38
	v_pk_fma_f32 v[34:35], v[34:35], v[74:75], v[140:141] op_sel_hi:[0,1,1]
	v_exp_f32_e32 v34, v34
	v_exp_f32_e32 v35, v35
	v_exp_f32_e32 v36, v36
	v_exp_f32_e32 v37, v37
	v_add_f32_e32 v34, 0x3b808081, v34
	v_add_f32_e32 v35, 0x3b808081, v35
	v_rcp_f32_e32 v34, v34
	v_rcp_f32_e32 v35, v35
	v_add_f32_e32 v36, 0x3b808081, v36
	v_mul_f32_e32 v124, v243, v175
	v_add_f32_e32 v37, 0x3b808081, v37
	v_rcp_f32_e32 v39, v36
	v_cvt_pk_u8_f32 v34, v34, 0, 0
	v_rcp_f32_e32 v38, v37
	v_cvt_pk_u8_f32 v35, v35, 1, v34
	v_mul_f32_e32 v34, v20, v124
	v_pk_fma_f32 v[36:37], v[34:35], v[72:73], v[152:153] op_sel_hi:[0,1,1]
	v_exp_f32_e32 v37, v37
	v_cvt_pk_u8_f32 v35, v39, 2, v35
	v_cvt_pk_u8_f32 v195, v38, 3, v35
	v_pk_fma_f32 v[38:39], v[34:35], v[70:71], v[150:151] op_sel_hi:[0,1,1]
	v_exp_f32_e32 v38, v38
	v_add_f32_e32 v35, 0x3b808081, v37
	v_exp_f32_e32 v37, v39
	v_exp_f32_e32 v36, v36
	v_add_f32_e32 v38, 0x3b808081, v38
	v_rcp_f32_e32 v38, v38
	v_add_f32_e32 v37, 0x3b808081, v37
	v_rcp_f32_e32 v35, v35
	v_rcp_f32_e32 v37, v37
	v_add_f32_e32 v36, 0x3b808081, v36
	v_rcp_f32_e32 v39, v36
	v_cvt_pk_u8_f32 v36, v38, 0, 0
	v_cvt_pk_u8_f32 v38, v37, 1, v36
	v_pk_fma_f32 v[36:37], v[34:35], v[68:69], v[148:149] op_sel_hi:[0,1,1]
	v_exp_f32_e32 v37, v37
	v_cvt_pk_u8_f32 v38, v39, 2, v38
	v_cvt_pk_u8_f32 v196, v35, 3, v38
	v_pk_fma_f32 v[38:39], v[34:35], v[66:67], v[146:147] op_sel_hi:[0,1,1]
	v_exp_f32_e32 v38, v38
	v_add_f32_e32 v35, 0x3b808081, v37
	v_exp_f32_e32 v37, v39
	v_exp_f32_e32 v36, v36
	v_add_f32_e32 v38, 0x3b808081, v38
	v_rcp_f32_e32 v38, v38
	v_add_f32_e32 v37, 0x3b808081, v37
	v_rcp_f32_e32 v35, v35
	v_rcp_f32_e32 v37, v37
	v_add_f32_e32 v36, 0x3b808081, v36
	v_rcp_f32_e32 v39, v36
	v_cvt_pk_u8_f32 v36, v38, 0, 0
	v_cvt_pk_u8_f32 v38, v37, 1, v36
	v_pk_fma_f32 v[36:37], v[34:35], v[64:65], v[144:145] op_sel_hi:[0,1,1]
	v_exp_f32_e32 v37, v37
	v_cvt_pk_u8_f32 v38, v39, 2, v38
	v_cvt_pk_u8_f32 v197, v35, 3, v38
	v_pk_fma_f32 v[38:39], v[34:35], v[62:63], v[142:143] op_sel_hi:[0,1,1]
	v_exp_f32_e32 v38, v38
	v_add_f32_e32 v35, 0x3b808081, v37
	v_exp_f32_e32 v37, v39
	v_exp_f32_e32 v36, v36
	v_add_f32_e32 v38, 0x3b808081, v38
	v_rcp_f32_e32 v38, v38
	v_add_f32_e32 v37, 0x3b808081, v37
	v_rcp_f32_e32 v37, v37
	v_add_f32_e32 v36, 0x3b808081, v36
	v_rcp_f32_e32 v39, v36
	v_rcp_f32_e32 v35, v35
	v_cvt_pk_u8_f32 v36, v38, 0, 0
	v_cvt_pk_u8_f32 v38, v37, 1, v36
	v_cvt_pk_u8_f32 v38, v39, 2, v38
	v_pk_fma_f32 v[36:37], v[34:35], v[60:61], v[138:139] op_sel_hi:[0,1,1]
	v_cvt_pk_u8_f32 v198, v35, 3, v38
	v_pk_fma_f32 v[34:35], v[34:35], v[58:59], v[140:141] op_sel_hi:[0,1,1]
	v_exp_f32_e32 v34, v34
	v_exp_f32_e32 v35, v35
	v_exp_f32_e32 v36, v36
	v_exp_f32_e32 v37, v37
	v_add_f32_e32 v34, 0x3b808081, v34
	v_add_f32_e32 v35, 0x3b808081, v35
	v_rcp_f32_e32 v34, v34
	v_rcp_f32_e32 v35, v35
	v_cvt_f32_i32_e32 v57, v57
	v_cvt_f32_i32_e32 v56, v56
	v_add_f32_e32 v36, 0x3b808081, v36
	v_mul_f32_e32 v123, v244, v176
	v_add_f32_e32 v37, 0x3b808081, v37
	v_rcp_f32_e32 v39, v36
	v_cvt_pk_u8_f32 v34, v34, 0, 0
	v_cvt_f32_i32_e32 v55, v55
	v_cvt_f32_i32_e32 v54, v54
	v_rcp_f32_e32 v38, v37
	v_cvt_pk_u8_f32 v35, v35, 1, v34
	v_mul_f32_e32 v34, v20, v123
	v_pk_fma_f32 v[36:37], v[34:35], v[56:57], v[152:153] op_sel_hi:[0,1,1]
	v_exp_f32_e32 v37, v37
	v_cvt_pk_u8_f32 v35, v39, 2, v35
	v_cvt_pk_u8_f32 v199, v38, 3, v35
	v_pk_fma_f32 v[38:39], v[34:35], v[54:55], v[150:151] op_sel_hi:[0,1,1]
	v_exp_f32_e32 v38, v38
	v_add_f32_e32 v35, 0x3b808081, v37
	v_exp_f32_e32 v37, v39
	v_exp_f32_e32 v36, v36
	v_add_f32_e32 v38, 0x3b808081, v38
	v_rcp_f32_e32 v38, v38
	v_add_f32_e32 v37, 0x3b808081, v37
	v_cvt_f32_i32_e32 v53, v53
	v_cvt_f32_i32_e32 v52, v52
	v_rcp_f32_e32 v35, v35
	v_rcp_f32_e32 v37, v37
	v_add_f32_e32 v36, 0x3b808081, v36
	v_rcp_f32_e32 v39, v36
	v_cvt_f32_i32_e32 v51, v51
	v_cvt_f32_i32_e32 v50, v50
	v_cvt_pk_u8_f32 v36, v38, 0, 0
	v_cvt_pk_u8_f32 v38, v37, 1, v36
	v_pk_fma_f32 v[36:37], v[34:35], v[52:53], v[148:149] op_sel_hi:[0,1,1]
	v_exp_f32_e32 v37, v37
	v_cvt_pk_u8_f32 v38, v39, 2, v38
	v_cvt_pk_u8_f32 v200, v35, 3, v38
	v_pk_fma_f32 v[38:39], v[34:35], v[50:51], v[146:147] op_sel_hi:[0,1,1]
	v_exp_f32_e32 v38, v38
	v_add_f32_e32 v35, 0x3b808081, v37
	v_exp_f32_e32 v37, v39
	v_exp_f32_e32 v36, v36
	v_add_f32_e32 v38, 0x3b808081, v38
	v_rcp_f32_e32 v38, v38
	v_add_f32_e32 v37, 0x3b808081, v37
	v_rcp_f32_e32 v35, v35
	v_rcp_f32_e32 v37, v37
	v_add_f32_e32 v36, 0x3b808081, v36
	v_rcp_f32_e32 v39, v36
	v_cvt_pk_u8_f32 v36, v38, 0, 0
	v_cvt_pk_u8_f32 v38, v37, 1, v36
	v_pk_fma_f32 v[36:37], v[34:35], v[48:49], v[144:145] op_sel_hi:[0,1,1]
	v_exp_f32_e32 v37, v37
	v_cvt_pk_u8_f32 v38, v39, 2, v38
	v_cvt_pk_u8_f32 v201, v35, 3, v38
	v_pk_fma_f32 v[38:39], v[34:35], v[46:47], v[142:143] op_sel_hi:[0,1,1]
	v_exp_f32_e32 v38, v38
	v_add_f32_e32 v35, 0x3b808081, v37
	v_exp_f32_e32 v37, v39
	v_exp_f32_e32 v36, v36
	v_add_f32_e32 v38, 0x3b808081, v38
	v_rcp_f32_e32 v38, v38
	v_add_f32_e32 v37, 0x3b808081, v37
	v_rcp_f32_e32 v37, v37
	v_add_f32_e32 v36, 0x3b808081, v36
	v_rcp_f32_e32 v39, v36
	v_rcp_f32_e32 v35, v35
	v_cvt_pk_u8_f32 v36, v38, 0, 0
	v_cvt_pk_u8_f32 v38, v37, 1, v36
	v_cvt_pk_u8_f32 v38, v39, 2, v38
	v_pk_fma_f32 v[36:37], v[34:35], v[44:45], v[138:139] op_sel_hi:[0,1,1]
	v_cvt_pk_u8_f32 v205, v35, 3, v38
	v_pk_fma_f32 v[34:35], v[34:35], v[42:43], v[140:141] op_sel_hi:[0,1,1]
	v_exp_f32_e32 v34, v34
	v_exp_f32_e32 v35, v35
	v_exp_f32_e32 v37, v37
	v_exp_f32_e32 v36, v36
	v_add_f32_e32 v34, 0x3b808081, v34
	v_add_f32_e32 v35, 0x3b808081, v35
	v_rcp_f32_e32 v34, v34
	v_rcp_f32_e32 v35, v35
	v_cvt_f32_i32_e32 v41, v41
	v_cvt_f32_i32_e32 v40, v40
	v_mul_f32_e32 v122, v245, v177
	v_cvt_pk_u8_f32 v34, v34, 0, 0
	v_add_f32_e32 v37, 0x3b808081, v37
	v_add_f32_e32 v36, 0x3b808081, v36
	v_cvt_pk_u8_f32 v35, v35, 1, v34
	v_mul_f32_e32 v34, v20, v122
	v_rcp_f32_e32 v38, v37
	v_rcp_f32_e32 v39, v36
	v_pk_fma_f32 v[36:37], v[34:35], v[40:41], v[152:153] op_sel_hi:[0,1,1]
	v_exp_f32_e32 v37, v37
	v_cvt_f32_i32_e32 v19, v19
	v_cvt_pk_u8_f32 v35, v39, 2, v35
	v_cvt_pk_u8_f32 v207, v38, 3, v35
	v_pk_fma_f32 v[32:33], v[34:35], v[32:33], v[150:151] op_sel_hi:[0,1,1]
	v_add_f32_e32 v35, 0x3b808081, v37
	v_cvt_f32_i32_e32 v18, v18
	v_rcp_f32_e32 v35, v35
	v_cvt_f32_i32_e32 v17, v17
	v_cvt_f32_i32_e32 v16, v16
	v_cvt_f32_i32_e32 v15, v15
	v_pk_fma_f32 v[18:19], v[34:35], v[18:19], v[140:141] op_sel_hi:[0,1,1]
	v_exp_f32_e32 v18, v18
	v_pk_fma_f32 v[22:23], v[34:35], v[22:23], v[138:139] op_sel_hi:[0,1,1]
	v_exp_f32_e32 v19, v19
	v_exp_f32_e32 v22, v22
	v_add_f32_e32 v18, 0x3b808081, v18
	v_rcp_f32_e32 v18, v18
	v_add_f32_e32 v19, 0x3b808081, v19
	v_rcp_f32_e32 v19, v19
	v_add_f32_e32 v22, 0x3b808081, v22
	v_rcp_f32_e32 v22, v22
	v_cvt_f32_i32_e32 v14, v14
	v_cvt_pk_u8_f32 v18, v18, 0, 0
	v_cvt_pk_u8_f32 v19, v19, 1, v18
	v_mul_f32_e32 v18, v20, v21
	v_pk_fma_f32 v[16:17], v[18:19], v[16:17], v[152:153] op_sel_hi:[0,1,1]
	v_cvt_pk_u8_f32 v19, v22, 2, v19
	v_pk_fma_f32 v[14:15], v[18:19], v[14:15], v[150:151] op_sel_hi:[0,1,1]
	v_exp_f32_e32 v14, v14
	v_exp_f32_e32 v15, v15
	v_exp_f32_e32 v16, v16
	v_cvt_f32_i32_e32 v3, v3
	v_add_f32_e32 v14, 0x3b808081, v14
	v_add_f32_e32 v15, 0x3b808081, v15
	v_rcp_f32_e32 v14, v14
	v_rcp_f32_e32 v15, v15
	v_add_f32_e32 v16, 0x3b808081, v16
	v_rcp_f32_e32 v16, v16
	v_cvt_pk_u8_f32 v14, v14, 0, 0
	v_cvt_pk_u8_f32 v14, v15, 1, v14
	v_cvt_f32_i32_e32 v2, v2
	v_cvt_f32_i32_e32 v13, v13
	v_cvt_f32_i32_e32 v12, v12
	v_cvt_pk_u8_f32 v16, v16, 2, v14
	v_cvt_f32_i32_e32 v15, v11
	v_cvt_f32_i32_e32 v14, v10
	v_cvt_f32_i32_e32 v7, v7
	v_cvt_f32_i32_e32 v6, v6
	v_cvt_f32_i32_e32 v5, v5
	v_cvt_f32_i32_e32 v4, v4
	v_cvt_f32_i32_e32 v9, v9
	v_cvt_f32_i32_e32 v8, v8
	v_pk_fma_f32 v[2:3], v[18:19], v[2:3], v[140:141] op_sel_hi:[0,1,1]
	v_pk_fma_f32 v[28:29], v[34:35], v[28:29], v[146:147] op_sel_hi:[0,1,1]
	v_pk_fma_f32 v[24:25], v[34:35], v[24:25], v[142:143] op_sel_hi:[0,1,1]
	v_pk_fma_f32 v[12:13], v[18:19], v[12:13], v[148:149] op_sel_hi:[0,1,1]
	v_pk_fma_f32 v[14:15], v[18:19], v[14:15], v[146:147] op_sel_hi:[0,1,1]
	v_pk_fma_f32 v[6:7], v[18:19], v[6:7], v[142:143] op_sel_hi:[0,1,1]
	v_exp_f32_e32 v2, v2
	v_exp_f32_e32 v32, v32
	v_exp_f32_e32 v28, v28
	v_exp_f32_e32 v24, v24
	v_exp_f32_e32 v11, v13
	v_exp_f32_e32 v13, v14
	v_exp_f32_e32 v6, v6
	v_pk_fma_f32 v[4:5], v[18:19], v[4:5], v[138:139] op_sel_hi:[0,1,1]
	v_exp_f32_e32 v3, v3
	v_exp_f32_e32 v33, v33
	v_pk_fma_f32 v[30:31], v[34:35], v[30:31], v[148:149] op_sel_hi:[0,1,1]
	v_exp_f32_e32 v29, v29
	v_pk_fma_f32 v[26:27], v[34:35], v[26:27], v[144:145] op_sel_hi:[0,1,1]
	v_exp_f32_e32 v25, v25
	v_exp_f32_e32 v14, v15
	v_pk_fma_f32 v[8:9], v[18:19], v[8:9], v[144:145] op_sel_hi:[0,1,1]
	v_exp_f32_e32 v7, v7
	v_exp_f32_e32 v4, v4
	v_exp_f32_e32 v36, v36
	v_exp_f32_e32 v30, v30
	v_exp_f32_e32 v26, v26
	v_exp_f32_e32 v12, v12
	v_exp_f32_e32 v8, v8
	v_exp_f32_e32 v5, v5
	v_exp_f32_e32 v31, v31
	v_exp_f32_e32 v27, v27
	v_exp_f32_e32 v23, v23
	v_exp_f32_e32 v17, v17
	v_exp_f32_e32 v9, v9
	v_add_f32_e32 v2, 0x3b808081, v2
	v_add_f32_e32 v32, 0x3b808081, v32
	v_add_f32_e32 v28, 0x3b808081, v28
	v_add_f32_e32 v24, 0x3b808081, v24
	v_add_f32_e32 v13, 0x3b808081, v13
	v_add_f32_e32 v6, 0x3b808081, v6
	v_add_f32_e32 v3, 0x3b808081, v3
	v_rcp_f32_e32 v2, v2
	v_add_f32_e32 v33, 0x3b808081, v33
	v_rcp_f32_e32 v32, v32
	v_add_f32_e32 v29, 0x3b808081, v29
	v_rcp_f32_e32 v28, v28
	v_add_f32_e32 v25, 0x3b808081, v25
	v_rcp_f32_e32 v24, v24
	v_rcp_f32_e32 v13, v13
	v_add_f32_e32 v14, 0x3b808081, v14
	v_add_f32_e32 v7, 0x3b808081, v7
	v_rcp_f32_e32 v6, v6
	v_add_f32_e32 v4, 0x3b808081, v4
	v_rcp_f32_e32 v3, v3
	v_rcp_f32_e32 v33, v33
	v_add_f32_e32 v36, 0x3b808081, v36
	v_rcp_f32_e32 v29, v29
	v_add_f32_e32 v30, 0x3b808081, v30
	v_rcp_f32_e32 v25, v25
	v_add_f32_e32 v26, 0x3b808081, v26
	v_add_f32_e32 v12, 0x3b808081, v12
	v_rcp_f32_e32 v14, v14
	v_rcp_f32_e32 v7, v7
	v_add_f32_e32 v8, 0x3b808081, v8
	v_add_f32_e32 v5, 0x3b808081, v5
	v_rcp_f32_e32 v4, v4
	v_rcp_f32_e32 v36, v36
	v_add_f32_e32 v31, 0x3b808081, v31
	v_rcp_f32_e32 v30, v30
	v_add_f32_e32 v27, 0x3b808081, v27
	v_rcp_f32_e32 v26, v26
	v_add_f32_e32 v23, 0x3b808081, v23
	v_add_f32_e32 v17, 0x3b808081, v17
	v_add_f32_e32 v11, 0x3b808081, v11
	v_rcp_f32_e32 v12, v12
	v_add_f32_e32 v9, 0x3b808081, v9
	v_rcp_f32_e32 v8, v8
	v_rcp_f32_e32 v5, v5
	v_rcp_f32_e32 v31, v31
	v_rcp_f32_e32 v27, v27
	v_rcp_f32_e32 v23, v23
	v_rcp_f32_e32 v17, v17
	v_rcp_f32_e32 v11, v11
	v_rcp_f32_e32 v9, v9
	v_cvt_pk_u8_f32 v2, v2, 0, 0
	v_cvt_pk_u8_f32 v32, v32, 0, 0
	v_cvt_pk_u8_f32 v28, v28, 0, 0
	v_cvt_pk_u8_f32 v24, v24, 0, 0
	v_cvt_pk_u8_f32 v13, v13, 0, 0
	v_cvt_pk_u8_f32 v6, v6, 0, 0
	v_cvt_pk_u8_f32 v2, v3, 1, v2
	v_cvt_pk_u8_f32 v32, v33, 1, v32
	v_cvt_pk_u8_f32 v28, v29, 1, v28
	v_cvt_pk_u8_f32 v24, v25, 1, v24
	v_cvt_pk_u8_f32 v13, v14, 1, v13
	v_cvt_pk_u8_f32 v6, v7, 1, v6
	v_cvt_pk_u8_f32 v2, v4, 2, v2
	v_cvt_pk_u8_f32 v32, v36, 2, v32
	v_cvt_pk_u8_f32 v28, v30, 2, v28
	v_cvt_pk_u8_f32 v24, v26, 2, v24
	v_cvt_pk_u8_f32 v12, v12, 2, v13
	v_cvt_pk_u8_f32 v6, v8, 2, v6
	v_cvt_pk_u8_f32 v13, v5, 3, v2
	v_lshl_add_u32 v2, v156, 4, 0
	v_cvt_pk_u8_f32 v208, v35, 3, v32
	v_cvt_pk_u8_f32 v209, v31, 3, v28
	v_cvt_pk_u8_f32 v210, v27, 3, v24
	v_cvt_pk_u8_f32 v211, v23, 3, v19
	v_cvt_pk_u8_f32 v10, v17, 3, v16
	v_cvt_pk_u8_f32 v11, v11, 3, v12
	v_cvt_pk_u8_f32 v12, v9, 3, v6
	v_add_u32_e32 v2, 0x24f80, v2
	ds_write_b128 v2, v[10:13]
	s_andn2_b64 vcc, exec, s[40:41]
	s_mov_b64 s[4:5], -1
	s_cbranch_vccnz .LBB0_1002

.LBB0_1096:
	s_cmp_eq_u32 s29, 28
	s_cselect_b32 s56, s50, s7
	s_cselect_b32 s57, s51, s21
	s_cselect_b32 s54, s52, s27
	s_cselect_b32 s55, s53, s28
	s_add_u32 s48, s56, 0x80
	s_addc_u32 s49, s57, 0
	s_add_i32 s76, 0, 0x10000
	s_add_i32 s77, 0, 0x14000
	v_add_u32_e32 v142, s76, v207
	v_add_u32_e32 v158, s77, v207
	s_waitcnt lgkmcnt(0)
	s_cmp_eq_u32 s29, 28
	s_cbranch_scc0 .Lop_nopf
	s_lshl_b32 s74, s6, 13
	s_add_u32 s74, s10, s74
	s_addc_u32 s75, s11, 0
	v_mbcnt_lo_u32_b32 v250, -1, 0
	v_mbcnt_hi_u32_b32 v250, -1, v250
	v_lshl_add_u32 v250, v250, 4, s62
	s_add_i32 m0, s62, 0x24f80
	s_nop 0
	global_load_lds_dwordx4 v250, s[74:75]
.Lop_nopf:
	ds_read_b128 v[130:133], v142
	ds_read_b128 v[134:137], v142 offset:1024
	ds_read_b128 v[138:141], v142 offset:2048
	ds_read_b128 v[142:145], v142 offset:3072
	ds_read_b128 v[146:149], v158
	ds_read_b128 v[150:153], v158 offset:1024
	ds_read_b128 v[154:157], v158 offset:2048
	ds_read_b128 v[158:161], v158 offset:3072
	s_mov_b64 s[74:75], s[46:47]
	ds_read_b128 v[162:165], v237
	ds_read_b128 v[166:169], v237 offset:1024
	ds_read_b128 v[170:173], v237 offset:2048
	ds_read_b128 v[174:177], v237 offset:3072
	ds_read_b128 v[178:181], v237 offset:4096
	ds_read_b128 v[182:185], v237 offset:5120
	ds_read_b128 v[188:191], v237 offset:6144
	ds_read_b128 v[192:195], v237 offset:7168
	s_add_i32 m0, s62, 0xc000
	v_lshl_add_u64 v[196:197], s[74:75], 0, v[186:187]
	s_add_u32 s74, s74, 0x40000
	s_addc_u32 s75, s75, 0
	global_load_lds_dwordx4 v[196:197], off
	s_add_i32 m0, s62, 0xe000
	v_lshl_add_u64 v[196:197], s[74:75], 0, v[186:187]
	global_load_lds_dwordx4 v[196:197], off
	s_waitcnt vmcnt(8)
	s_waitcnt lgkmcnt(0)
	s_barrier
	s_setprio 1
	s_waitcnt lgkmcnt(0)
	v_mfma_f32_16x16x32_bf16 v[2:5], v[130:133], v[162:165], v[2:5]
	v_mfma_f32_16x16x32_bf16 v[6:9], v[138:141], v[162:165], v[6:9]
	v_mfma_f32_16x16x32_bf16 v[14:17], v[130:133], v[170:173], v[14:17]
	v_mfma_f32_16x16x32_bf16 v[22:25], v[138:141], v[170:173], v[22:25]
	v_mfma_f32_16x16x32_bf16 v[30:33], v[130:133], v[178:181], v[30:33]
	v_mfma_f32_16x16x32_bf16 v[38:41], v[138:141], v[178:181], v[38:41]
	v_mfma_f32_16x16x32_bf16 v[46:49], v[130:133], v[188:191], v[46:49]
	v_mfma_f32_16x16x32_bf16 v[54:57], v[138:141], v[188:191], v[54:57]
	v_mfma_f32_16x16x32_bf16 v[2:5], v[134:137], v[166:169], v[2:5]
	v_mfma_f32_16x16x32_bf16 v[6:9], v[142:145], v[166:169], v[6:9]
	v_mfma_f32_16x16x32_bf16 v[14:17], v[134:137], v[174:177], v[14:17]
	v_mfma_f32_16x16x32_bf16 v[22:25], v[142:145], v[174:177], v[22:25]
	v_mfma_f32_16x16x32_bf16 v[30:33], v[134:137], v[182:185], v[30:33]
	v_mfma_f32_16x16x32_bf16 v[38:41], v[142:145], v[182:185], v[38:41]
	v_mfma_f32_16x16x32_bf16 v[46:49], v[134:137], v[192:195], v[46:49]
	v_mfma_f32_16x16x32_bf16 v[54:57], v[142:145], v[192:195], v[54:57]
	s_setprio 0
	s_setprio 1
	v_mfma_f32_16x16x32_bf16 v[10:13], v[146:149], v[162:165], v[10:13]
	v_mfma_f32_16x16x32_bf16 v[18:21], v[154:157], v[162:165], v[18:21]
	v_mfma_f32_16x16x32_bf16 v[26:29], v[146:149], v[170:173], v[26:29]
	v_mfma_f32_16x16x32_bf16 v[34:37], v[154:157], v[170:173], v[34:37]
	v_mfma_f32_16x16x32_bf16 v[42:45], v[146:149], v[178:181], v[42:45]
	v_mfma_f32_16x16x32_bf16 v[50:53], v[154:157], v[178:181], v[50:53]
	v_mfma_f32_16x16x32_bf16 v[58:61], v[146:149], v[188:191], v[58:61]
	v_mfma_f32_16x16x32_bf16 v[62:65], v[154:157], v[188:191], v[62:65]
	v_mfma_f32_16x16x32_bf16 v[10:13], v[150:153], v[166:169], v[10:13]
	v_mfma_f32_16x16x32_bf16 v[18:21], v[158:161], v[166:169], v[18:21]
	v_mfma_f32_16x16x32_bf16 v[26:29], v[150:153], v[174:177], v[26:29]
	v_mfma_f32_16x16x32_bf16 v[34:37], v[158:161], v[174:177], v[34:37]
	v_mfma_f32_16x16x32_bf16 v[42:45], v[150:153], v[182:185], v[42:45]
	v_mfma_f32_16x16x32_bf16 v[50:53], v[158:161], v[182:185], v[50:53]
	v_mfma_f32_16x16x32_bf16 v[58:61], v[150:153], v[192:195], v[58:61]
	v_mfma_f32_16x16x32_bf16 v[62:65], v[158:161], v[192:195], v[62:65]
	s_setprio 0
	s_barrier
	s_mov_b64 s[74:75], s[54:55]
	ds_read_b128 v[162:165], v237 offset:16384
	ds_read_b128 v[166:169], v237 offset:17408
	ds_read_b128 v[170:173], v237 offset:18432
	ds_read_b128 v[174:177], v237 offset:19456
	ds_read_b128 v[178:181], v237 offset:20480
	ds_read_b128 v[182:185], v237 offset:21504
	ds_read_b128 v[188:191], v237 offset:22528
	ds_read_b128 v[192:195], v237 offset:23552
	s_add_i32 s76, s76, s61
	v_lshl_add_u64 v[196:197], s[74:75], 0, v[202:203]
	s_add_u32 s74, s74, 0x40000
	s_mov_b32 m0, s76
	s_addc_u32 s75, s75, 0
	global_load_lds_dwordx4 v[196:197], off
	s_add_i32 m0, s76, 0x2000
	v_lshl_add_u64 v[196:197], s[74:75], 0, v[202:203]
	s_add_u32 s74, s54, 0x80000
	s_addc_u32 s75, s55, 0
	global_load_lds_dwordx4 v[196:197], off
	s_add_i32 s76, s77, s61
	v_lshl_add_u64 v[196:197], s[74:75], 0, v[202:203]
	s_add_u32 s74, s74, 0x40000
	s_mov_b32 m0, s76
	s_addc_u32 s75, s75, 0
	global_load_lds_dwordx4 v[196:197], off
	s_add_i32 m0, s76, 0x2000
	v_lshl_add_u64 v[196:197], s[74:75], 0, v[202:203]
	s_mov_b64 s[74:75], s[56:57]
	global_load_lds_dwordx4 v[196:197], off
	s_mov_b32 m0, s62
	v_lshl_add_u64 v[196:197], s[74:75], 0, v[186:187]
	s_add_u32 s74, s74, 0x40000
	s_addc_u32 s75, s75, 0
	global_load_lds_dwordx4 v[196:197], off
	s_mov_b32 m0, s63
	v_lshl_add_u64 v[196:197], s[74:75], 0, v[186:187]
	global_load_lds_dwordx4 v[196:197], off
	s_waitcnt vmcnt(8)
	s_waitcnt lgkmcnt(0)
	s_barrier
	s_setprio 1
	s_waitcnt lgkmcnt(0)
	v_mfma_f32_16x16x32_bf16 v[66:69], v[130:133], v[162:165], v[66:69]
	v_mfma_f32_16x16x32_bf16 v[70:73], v[138:141], v[162:165], v[70:73]
	v_mfma_f32_16x16x32_bf16 v[74:77], v[130:133], v[170:173], v[74:77]
	v_mfma_f32_16x16x32_bf16 v[78:81], v[138:141], v[170:173], v[78:81]
	v_mfma_f32_16x16x32_bf16 v[86:89], v[130:133], v[178:181], v[86:89]
	v_mfma_f32_16x16x32_bf16 v[94:97], v[138:141], v[178:181], v[94:97]
	v_mfma_f32_16x16x32_bf16 v[102:105], v[130:133], v[188:191], v[102:105]
	v_mfma_f32_16x16x32_bf16 v[110:113], v[138:141], v[188:191], v[110:113]
	v_mfma_f32_16x16x32_bf16 v[66:69], v[134:137], v[166:169], v[66:69]
	v_mfma_f32_16x16x32_bf16 v[70:73], v[142:145], v[166:169], v[70:73]
	v_mfma_f32_16x16x32_bf16 v[74:77], v[134:137], v[174:177], v[74:77]
	v_mfma_f32_16x16x32_bf16 v[78:81], v[142:145], v[174:177], v[78:81]
	v_mfma_f32_16x16x32_bf16 v[86:89], v[134:137], v[182:185], v[86:89]
	v_mfma_f32_16x16x32_bf16 v[94:97], v[142:145], v[182:185], v[94:97]
	v_mfma_f32_16x16x32_bf16 v[102:105], v[134:137], v[192:195], v[102:105]
	v_mfma_f32_16x16x32_bf16 v[110:113], v[142:145], v[192:195], v[110:113]
	s_setprio 0
	s_setprio 1
	v_mfma_f32_16x16x32_bf16 v[82:85], v[146:149], v[162:165], v[82:85]
	v_mfma_f32_16x16x32_bf16 v[90:93], v[154:157], v[162:165], v[90:93]
	v_mfma_f32_16x16x32_bf16 v[98:101], v[146:149], v[170:173], v[98:101]
	v_mfma_f32_16x16x32_bf16 v[106:109], v[154:157], v[170:173], v[106:109]
	v_mfma_f32_16x16x32_bf16 v[114:117], v[146:149], v[178:181], v[114:117]
	v_mfma_f32_16x16x32_bf16 v[118:121], v[154:157], v[178:181], v[118:121]
	v_mfma_f32_16x16x32_bf16 v[122:125], v[146:149], v[188:191], v[122:125]
	v_mfma_f32_16x16x32_bf16 v[126:129], v[154:157], v[188:191], v[126:129]
	v_mfma_f32_16x16x32_bf16 v[82:85], v[150:153], v[166:169], v[82:85]
	v_mfma_f32_16x16x32_bf16 v[90:93], v[158:161], v[166:169], v[90:93]
	v_mfma_f32_16x16x32_bf16 v[98:101], v[150:153], v[174:177], v[98:101]
	v_mfma_f32_16x16x32_bf16 v[106:109], v[158:161], v[174:177], v[106:109]
	v_mfma_f32_16x16x32_bf16 v[114:117], v[150:153], v[182:185], v[114:117]
	v_mfma_f32_16x16x32_bf16 v[118:121], v[158:161], v[182:185], v[118:121]
	v_mfma_f32_16x16x32_bf16 v[122:125], v[150:153], v[192:195], v[122:125]
	v_mfma_f32_16x16x32_bf16 v[126:129], v[158:161], v[192:195], v[126:129]
	s_setprio 0
	s_barrier
	s_add_i32 s74, 0, 0x18000
	s_add_i32 s75, 0, 0x1c000
	v_add_u32_e32 v142, s74, v207
	v_add_u32_e32 v158, s75, v207
	ds_read_b128 v[130:133], v142
	ds_read_b128 v[134:137], v142 offset:1024
	ds_read_b128 v[138:141], v142 offset:2048
	ds_read_b128 v[142:145], v142 offset:3072
	ds_read_b128 v[146:149], v158
	ds_read_b128 v[150:153], v158 offset:1024
	ds_read_b128 v[154:157], v158 offset:2048
	ds_read_b128 v[158:161], v158 offset:3072
	s_add_u32 s56, s56, 0x80000
	s_addc_u32 s57, s57, 0
	ds_read_b128 v[162:165], v237 offset:32768
	ds_read_b128 v[166:169], v237 offset:33792
	ds_read_b128 v[170:173], v237 offset:34816
	ds_read_b128 v[174:177], v237 offset:35840
	ds_read_b128 v[178:181], v237 offset:36864
	ds_read_b128 v[182:185], v237 offset:37888
	ds_read_b128 v[188:191], v237 offset:38912
	ds_read_b128 v[192:195], v237 offset:39936
	s_mov_b32 m0, s64
	v_lshl_add_u64 v[196:197], s[56:57], 0, v[186:187]
	s_add_u32 s56, s56, 0x40000
	s_addc_u32 s57, s57, 0
	global_load_lds_dwordx4 v[196:197], off
	s_mov_b32 m0, s65
	v_lshl_add_u64 v[196:197], s[56:57], 0, v[186:187]
	global_load_lds_dwordx4 v[196:197], off
	s_waitcnt vmcnt(8)
	s_waitcnt lgkmcnt(0)
	s_barrier
	s_setprio 1
	s_waitcnt lgkmcnt(0)
	v_mfma_f32_16x16x32_bf16 v[2:5], v[130:133], v[162:165], v[2:5]
	v_mfma_f32_16x16x32_bf16 v[6:9], v[138:141], v[162:165], v[6:9]
	v_mfma_f32_16x16x32_bf16 v[14:17], v[130:133], v[170:173], v[14:17]
	v_mfma_f32_16x16x32_bf16 v[22:25], v[138:141], v[170:173], v[22:25]
	v_mfma_f32_16x16x32_bf16 v[30:33], v[130:133], v[178:181], v[30:33]
	v_mfma_f32_16x16x32_bf16 v[38:41], v[138:141], v[178:181], v[38:41]
	v_mfma_f32_16x16x32_bf16 v[46:49], v[130:133], v[188:191], v[46:49]
	v_mfma_f32_16x16x32_bf16 v[54:57], v[138:141], v[188:191], v[54:57]
	v_mfma_f32_16x16x32_bf16 v[2:5], v[134:137], v[166:169], v[2:5]
	v_mfma_f32_16x16x32_bf16 v[6:9], v[142:145], v[166:169], v[6:9]
	v_mfma_f32_16x16x32_bf16 v[14:17], v[134:137], v[174:177], v[14:17]
	v_mfma_f32_16x16x32_bf16 v[22:25], v[142:145], v[174:177], v[22:25]
	v_mfma_f32_16x16x32_bf16 v[30:33], v[134:137], v[182:185], v[30:33]
	v_mfma_f32_16x16x32_bf16 v[38:41], v[142:145], v[182:185], v[38:41]
	v_mfma_f32_16x16x32_bf16 v[46:49], v[134:137], v[192:195], v[46:49]
	v_mfma_f32_16x16x32_bf16 v[54:57], v[142:145], v[192:195], v[54:57]
	s_setprio 0
	s_setprio 1
	v_mfma_f32_16x16x32_bf16 v[10:13], v[146:149], v[162:165], v[10:13]
	v_mfma_f32_16x16x32_bf16 v[18:21], v[154:157], v[162:165], v[18:21]
	v_mfma_f32_16x16x32_bf16 v[26:29], v[146:149], v[170:173], v[26:29]
	v_mfma_f32_16x16x32_bf16 v[34:37], v[154:157], v[170:173], v[34:37]
	v_mfma_f32_16x16x32_bf16 v[42:45], v[146:149], v[178:181], v[42:45]
	v_mfma_f32_16x16x32_bf16 v[50:53], v[154:157], v[178:181], v[50:53]
	v_mfma_f32_16x16x32_bf16 v[58:61], v[146:149], v[188:191], v[58:61]
	v_mfma_f32_16x16x32_bf16 v[62:65], v[154:157], v[188:191], v[62:65]
	v_mfma_f32_16x16x32_bf16 v[10:13], v[150:153], v[166:169], v[10:13]
	v_mfma_f32_16x16x32_bf16 v[18:21], v[158:161], v[166:169], v[18:21]
	v_mfma_f32_16x16x32_bf16 v[26:29], v[150:153], v[174:177], v[26:29]
	v_mfma_f32_16x16x32_bf16 v[34:37], v[158:161], v[174:177], v[34:37]
	v_mfma_f32_16x16x32_bf16 v[42:45], v[150:153], v[182:185], v[42:45]
	v_mfma_f32_16x16x32_bf16 v[50:53], v[158:161], v[182:185], v[50:53]
	v_mfma_f32_16x16x32_bf16 v[58:61], v[150:153], v[192:195], v[58:61]
	v_mfma_f32_16x16x32_bf16 v[62:65], v[158:161], v[192:195], v[62:65]
	s_setprio 0
	s_barrier
	s_add_u32 s56, s54, 0x80
	s_addc_u32 s57, s55, 0
	ds_read_b128 v[162:165], v237 offset:49152
	ds_read_b128 v[166:169], v237 offset:50176
	ds_read_b128 v[170:173], v237 offset:51200
	ds_read_b128 v[174:177], v237 offset:52224
	ds_read_b128 v[178:181], v237 offset:53248
	ds_read_b128 v[182:185], v237 offset:54272
	ds_read_b128 v[188:191], v237 offset:55296
	ds_read_b128 v[192:195], v237 offset:56320
	s_add_i32 s74, s74, s61
	v_lshl_add_u64 v[196:197], s[56:57], 0, v[202:203]
	s_mov_b32 m0, s74
	s_add_u32 s56, s56, 0x40000
	global_load_lds_dwordx4 v[196:197], off
	s_addc_u32 s57, s57, 0
	s_add_i32 m0, s74, 0x2000
	s_add_u32 s54, s54, 0x80080
	s_addc_u32 s55, s55, 0
	v_lshl_add_u64 v[196:197], s[56:57], 0, v[202:203]
	global_load_lds_dwordx4 v[196:197], off
	s_add_i32 s56, s75, s61
	v_lshl_add_u64 v[196:197], s[54:55], 0, v[202:203]
	s_add_u32 s54, s54, 0x40000
	s_mov_b32 m0, s56
	s_addc_u32 s55, s55, 0
	global_load_lds_dwordx4 v[196:197], off
	s_add_i32 m0, s56, 0x2000
	v_lshl_add_u64 v[196:197], s[54:55], 0, v[202:203]
	global_load_lds_dwordx4 v[196:197], off
	s_mov_b32 m0, s66
	v_lshl_add_u64 v[196:197], s[48:49], 0, v[186:187]
	s_add_u32 s48, s48, 0x40000
	s_addc_u32 s49, s49, 0
	global_load_lds_dwordx4 v[196:197], off
	s_mov_b32 m0, s67
	v_lshl_add_u64 v[196:197], s[48:49], 0, v[186:187]
	global_load_lds_dwordx4 v[196:197], off
	s_waitcnt vmcnt(8)
	s_waitcnt lgkmcnt(0)
	s_barrier
	s_setprio 1
	s_waitcnt lgkmcnt(0)
	v_mfma_f32_16x16x32_bf16 v[66:69], v[130:133], v[162:165], v[66:69]
	v_mfma_f32_16x16x32_bf16 v[70:73], v[138:141], v[162:165], v[70:73]
	v_mfma_f32_16x16x32_bf16 v[74:77], v[130:133], v[170:173], v[74:77]
	v_mfma_f32_16x16x32_bf16 v[78:81], v[138:141], v[170:173], v[78:81]
	v_mfma_f32_16x16x32_bf16 v[86:89], v[130:133], v[178:181], v[86:89]
	v_mfma_f32_16x16x32_bf16 v[94:97], v[138:141], v[178:181], v[94:97]
	v_mfma_f32_16x16x32_bf16 v[102:105], v[130:133], v[188:191], v[102:105]
	v_mfma_f32_16x16x32_bf16 v[110:113], v[138:141], v[188:191], v[110:113]
	v_mfma_f32_16x16x32_bf16 v[66:69], v[134:137], v[166:169], v[66:69]
	v_mfma_f32_16x16x32_bf16 v[70:73], v[142:145], v[166:169], v[70:73]
	v_mfma_f32_16x16x32_bf16 v[74:77], v[134:137], v[174:177], v[74:77]
	v_mfma_f32_16x16x32_bf16 v[78:81], v[142:145], v[174:177], v[78:81]
	v_mfma_f32_16x16x32_bf16 v[86:89], v[134:137], v[182:185], v[86:89]
	v_mfma_f32_16x16x32_bf16 v[94:97], v[142:145], v[182:185], v[94:97]
	v_mfma_f32_16x16x32_bf16 v[102:105], v[134:137], v[192:195], v[102:105]
	v_mfma_f32_16x16x32_bf16 v[110:113], v[142:145], v[192:195], v[110:113]
	s_setprio 0
	s_setprio 1
	v_mfma_f32_16x16x32_bf16 v[82:85], v[146:149], v[162:165], v[82:85]
	v_mfma_f32_16x16x32_bf16 v[90:93], v[154:157], v[162:165], v[90:93]
	v_mfma_f32_16x16x32_bf16 v[98:101], v[146:149], v[170:173], v[98:101]
	v_mfma_f32_16x16x32_bf16 v[106:109], v[154:157], v[170:173], v[106:109]
	v_mfma_f32_16x16x32_bf16 v[114:117], v[146:149], v[178:181], v[114:117]
	v_mfma_f32_16x16x32_bf16 v[118:121], v[154:157], v[178:181], v[118:121]
	v_mfma_f32_16x16x32_bf16 v[122:125], v[146:149], v[188:191], v[122:125]
	v_mfma_f32_16x16x32_bf16 v[126:129], v[154:157], v[188:191], v[126:129]
	v_mfma_f32_16x16x32_bf16 v[82:85], v[150:153], v[166:169], v[82:85]
	v_mfma_f32_16x16x32_bf16 v[90:93], v[158:161], v[166:169], v[90:93]
	v_mfma_f32_16x16x32_bf16 v[98:101], v[150:153], v[174:177], v[98:101]
	v_mfma_f32_16x16x32_bf16 v[106:109], v[158:161], v[174:177], v[106:109]
	v_mfma_f32_16x16x32_bf16 v[114:117], v[150:153], v[182:185], v[114:117]
	v_mfma_f32_16x16x32_bf16 v[118:121], v[158:161], v[182:185], v[118:121]
	v_mfma_f32_16x16x32_bf16 v[122:125], v[150:153], v[192:195], v[122:125]
	v_mfma_f32_16x16x32_bf16 v[126:129], v[158:161], v[192:195], v[126:129]
	s_setprio 0
	s_barrier
	s_add_i32 s29, s29, 2
	s_add_u32 s7, s7, 0x100
	s_addc_u32 s21, s21, 0
	s_add_u32 s27, s27, 0x100
	s_addc_u32 s28, s28, 0
	s_add_u32 s46, s46, 0x100
	s_addc_u32 s47, s47, 0
	s_cmp_gt_u32 s29, 29
	s_cbranch_scc0 .LBB0_1096
	s_and_b64 vcc, exec, s[18:19]
	s_cbranch_vccz .LBB0_1099
	s_barrier
.LBB0_1099:
	v_lshl_add_u32 v208, s6, 8, v205
	v_ashrrev_i32_e32 v209, 31, v208
	v_or_b32_e32 v200, 16, v208
	v_ashrrev_i32_e32 v201, 31, v200
	v_lshlrev_b32_e32 v250, 5, v205
	v_add_u32_e32 v250, 0x24f80, v250
	ds_read_b128 v[238:241], v250 offset:16
	ds_read_b128 v[242:245], v250
	v_or_b32_e32 v198, 32, v208
	v_ashrrev_i32_e32 v199, 31, v198
	ds_read_b128 v[178:181], v250 offset:528
	ds_read_b128 v[182:185], v250 offset:512
	v_or_b32_e32 v196, 48, v208
	v_ashrrev_i32_e32 v197, 31, v196
	ds_read_b128 v[170:173], v250 offset:1040
	ds_read_b128 v[174:177], v250 offset:1024
	v_add_u32_e32 v194, 0x80, v208
	v_ashrrev_i32_e32 v195, 31, v194
	ds_read_b128 v[162:165], v250 offset:1552
	ds_read_b128 v[166:169], v250 offset:1536
	v_add_u32_e32 v192, 0x90, v208
	v_ashrrev_i32_e32 v193, 31, v192
	ds_read_b128 v[154:157], v250 offset:4112
	ds_read_b128 v[158:161], v250 offset:4096
	v_add_u32_e32 v190, 0xa0, v208
	v_ashrrev_i32_e32 v191, 31, v190
	ds_read_b128 v[146:149], v250 offset:4624
	ds_read_b128 v[150:153], v250 offset:4608
	v_add_u32_e32 v188, 0xb0, v208
	v_ashrrev_i32_e32 v189, 31, v188
	ds_read_b128 v[138:141], v250 offset:5136
	ds_read_b128 v[142:145], v250 offset:5120
	ds_read_b128 v[130:133], v250 offset:5648
	ds_read_b128 v[134:137], v250 offset:5632
	s_cmp_eq_u32 s26, 0
	s_cselect_b64 s[28:29], -1, 0
	s_and_b64 s[46:47], s[42:43], s[28:29]
	s_waitcnt lgkmcnt(0)
	v_max_f32_e32 v241, v241, v241
	v_max_f32_e32 v240, v240, v240
	v_max_f32_e32 v243, v243, v243
	v_max_f32_e32 v242, v242, v242
	v_max_f32_e32 v245, v245, v245
	v_max_f32_e32 v244, v244, v244
	v_max_f32_e32 v240, v240, v241
	v_max_f32_e32 v242, v242, v243
	v_max_f32_e32 v243, v244, v245
	v_max3_f32 v238, v238, v239, v240
	v_max3_f32 v238, v242, v243, v238
	v_fmamk_f32 v238, v238, 0x3c077551, v231
	s_and_saveexec_b64 s[48:49], s[46:47]
	s_cbranch_execz .LBB0_1101
	v_lshl_add_u64 v[240:241], v[208:209], 2, s[14:15]
	global_store_dword v[240:241], v238, off

.LBB0_1286:
	s_cmpk_eq_i32 s71, 0x54
	s_cselect_b32 s54, s48, s9
	s_cselect_b32 s55, s49, s27
	s_cselect_b32 s52, s50, s28
	s_cselect_b32 s53, s51, s29
	s_add_u32 s46, s54, 0x80
	s_addc_u32 s47, s55, 0
	s_add_i32 s74, 0, 0x10000
	s_add_i32 s75, 0, 0x14000
	v_add_u32_e32 v142, s74, v207
	v_add_u32_e32 v158, s75, v207
	s_waitcnt lgkmcnt(0)
	s_cmpk_eq_i32 s71, 0x54
	s_cbranch_scc0 .Lfd_nopf
	s_lshl_b32 s72, s8, 13
	s_add_u32 s72, s14, s72
	s_addc_u32 s73, s15, 0
	v_mbcnt_lo_u32_b32 v250, -1, 0
	v_mbcnt_hi_u32_b32 v250, -1, v250
	v_lshl_add_u32 v250, v250, 4, s58
	s_add_i32 m0, s58, 0x24f80
	s_nop 0
	global_load_lds_dwordx4 v250, s[72:73]
.Lfd_nopf:
	ds_read_b128 v[130:133], v142
	ds_read_b128 v[134:137], v142 offset:1024
	ds_read_b128 v[138:141], v142 offset:2048
	ds_read_b128 v[142:145], v142 offset:3072
	ds_read_b128 v[146:149], v158
	ds_read_b128 v[150:153], v158 offset:1024
	ds_read_b128 v[154:157], v158 offset:2048
	ds_read_b128 v[158:161], v158 offset:3072
	s_mov_b64 s[72:73], s[44:45]
	ds_read_b128 v[162:165], v237
	ds_read_b128 v[166:169], v237 offset:1024
	ds_read_b128 v[170:173], v237 offset:2048
	ds_read_b128 v[174:177], v237 offset:3072
	ds_read_b128 v[178:181], v237 offset:4096
	ds_read_b128 v[182:185], v237 offset:5120
	ds_read_b128 v[188:191], v237 offset:6144
	ds_read_b128 v[192:195], v237 offset:7168
	s_add_i32 m0, s58, 0xc000
	v_lshl_add_u64 v[196:197], s[72:73], 0, v[186:187]
	s_add_u32 s72, s72, 0xb0000
	s_addc_u32 s73, s73, 0
	global_load_lds_dwordx4 v[196:197], off
	s_add_i32 m0, s58, 0xe000
	v_lshl_add_u64 v[196:197], s[72:73], 0, v[186:187]
	global_load_lds_dwordx4 v[196:197], off
	s_waitcnt vmcnt(8)
	s_waitcnt lgkmcnt(0)
	s_barrier
	s_setprio 1
	s_waitcnt lgkmcnt(0)
	v_mfma_f32_16x16x32_bf16 v[2:5], v[130:133], v[162:165], v[2:5]
	v_mfma_f32_16x16x32_bf16 v[6:9], v[138:141], v[162:165], v[6:9]
	v_mfma_f32_16x16x32_bf16 v[14:17], v[130:133], v[170:173], v[14:17]
	v_mfma_f32_16x16x32_bf16 v[22:25], v[138:141], v[170:173], v[22:25]
	v_mfma_f32_16x16x32_bf16 v[30:33], v[130:133], v[178:181], v[30:33]
	v_mfma_f32_16x16x32_bf16 v[38:41], v[138:141], v[178:181], v[38:41]
	v_mfma_f32_16x16x32_bf16 v[46:49], v[130:133], v[188:191], v[46:49]
	v_mfma_f32_16x16x32_bf16 v[54:57], v[138:141], v[188:191], v[54:57]
	v_mfma_f32_16x16x32_bf16 v[2:5], v[134:137], v[166:169], v[2:5]
	v_mfma_f32_16x16x32_bf16 v[6:9], v[142:145], v[166:169], v[6:9]
	v_mfma_f32_16x16x32_bf16 v[14:17], v[134:137], v[174:177], v[14:17]
	v_mfma_f32_16x16x32_bf16 v[22:25], v[142:145], v[174:177], v[22:25]
	v_mfma_f32_16x16x32_bf16 v[30:33], v[134:137], v[182:185], v[30:33]
	v_mfma_f32_16x16x32_bf16 v[38:41], v[142:145], v[182:185], v[38:41]
	v_mfma_f32_16x16x32_bf16 v[46:49], v[134:137], v[192:195], v[46:49]
	v_mfma_f32_16x16x32_bf16 v[54:57], v[142:145], v[192:195], v[54:57]
	s_setprio 0
	s_setprio 1
	v_mfma_f32_16x16x32_bf16 v[10:13], v[146:149], v[162:165], v[10:13]
	v_mfma_f32_16x16x32_bf16 v[18:21], v[154:157], v[162:165], v[18:21]
	v_mfma_f32_16x16x32_bf16 v[26:29], v[146:149], v[170:173], v[26:29]
	v_mfma_f32_16x16x32_bf16 v[34:37], v[154:157], v[170:173], v[34:37]
	v_mfma_f32_16x16x32_bf16 v[42:45], v[146:149], v[178:181], v[42:45]
	v_mfma_f32_16x16x32_bf16 v[50:53], v[154:157], v[178:181], v[50:53]
	v_mfma_f32_16x16x32_bf16 v[58:61], v[146:149], v[188:191], v[58:61]
	v_mfma_f32_16x16x32_bf16 v[62:65], v[154:157], v[188:191], v[62:65]
	v_mfma_f32_16x16x32_bf16 v[10:13], v[150:153], v[166:169], v[10:13]
	v_mfma_f32_16x16x32_bf16 v[18:21], v[158:161], v[166:169], v[18:21]
	v_mfma_f32_16x16x32_bf16 v[26:29], v[150:153], v[174:177], v[26:29]
	v_mfma_f32_16x16x32_bf16 v[34:37], v[158:161], v[174:177], v[34:37]
	v_mfma_f32_16x16x32_bf16 v[42:45], v[150:153], v[182:185], v[42:45]
	v_mfma_f32_16x16x32_bf16 v[50:53], v[158:161], v[182:185], v[50:53]
	v_mfma_f32_16x16x32_bf16 v[58:61], v[150:153], v[192:195], v[58:61]
	v_mfma_f32_16x16x32_bf16 v[62:65], v[158:161], v[192:195], v[62:65]
	s_setprio 0
	s_barrier
	s_mov_b64 s[72:73], s[52:53]
	ds_read_b128 v[162:165], v237 offset:16384
	ds_read_b128 v[166:169], v237 offset:17408
	ds_read_b128 v[170:173], v237 offset:18432
	ds_read_b128 v[174:177], v237 offset:19456
	ds_read_b128 v[178:181], v237 offset:20480
	ds_read_b128 v[182:185], v237 offset:21504
	ds_read_b128 v[188:191], v237 offset:22528
	ds_read_b128 v[192:195], v237 offset:23552
	s_add_i32 s74, s74, s57
	v_lshl_add_u64 v[196:197], s[72:73], 0, v[202:203]
	s_add_u32 s72, s72, 0xb0000
	s_mov_b32 m0, s74
	s_addc_u32 s73, s73, 0
	global_load_lds_dwordx4 v[196:197], off
	s_add_i32 m0, s74, 0x2000
	v_lshl_add_u64 v[196:197], s[72:73], 0, v[202:203]
	s_add_u32 s72, s52, 0x160000
	s_addc_u32 s73, s53, 0
	global_load_lds_dwordx4 v[196:197], off
	s_add_i32 s74, s75, s57
	v_lshl_add_u64 v[196:197], s[72:73], 0, v[202:203]
	s_add_u32 s72, s72, 0xb0000
	s_mov_b32 m0, s74
	s_addc_u32 s73, s73, 0
	global_load_lds_dwordx4 v[196:197], off
	s_add_i32 m0, s74, 0x2000
	v_lshl_add_u64 v[196:197], s[72:73], 0, v[202:203]
	s_mov_b64 s[72:73], s[54:55]
	global_load_lds_dwordx4 v[196:197], off
	s_mov_b32 m0, s58
	v_lshl_add_u64 v[196:197], s[72:73], 0, v[186:187]
	s_add_u32 s72, s72, 0xb0000
	s_addc_u32 s73, s73, 0
	global_load_lds_dwordx4 v[196:197], off
	s_mov_b32 m0, s59
	v_lshl_add_u64 v[196:197], s[72:73], 0, v[186:187]
	global_load_lds_dwordx4 v[196:197], off
	s_waitcnt vmcnt(8)
	s_waitcnt lgkmcnt(0)
	s_barrier
	s_setprio 1
	s_waitcnt lgkmcnt(0)
	v_mfma_f32_16x16x32_bf16 v[66:69], v[130:133], v[162:165], v[66:69]
	v_mfma_f32_16x16x32_bf16 v[70:73], v[138:141], v[162:165], v[70:73]
	v_mfma_f32_16x16x32_bf16 v[74:77], v[130:133], v[170:173], v[74:77]
	v_mfma_f32_16x16x32_bf16 v[78:81], v[138:141], v[170:173], v[78:81]
	v_mfma_f32_16x16x32_bf16 v[86:89], v[130:133], v[178:181], v[86:89]
	v_mfma_f32_16x16x32_bf16 v[94:97], v[138:141], v[178:181], v[94:97]
	v_mfma_f32_16x16x32_bf16 v[102:105], v[130:133], v[188:191], v[102:105]
	v_mfma_f32_16x16x32_bf16 v[110:113], v[138:141], v[188:191], v[110:113]
	v_mfma_f32_16x16x32_bf16 v[66:69], v[134:137], v[166:169], v[66:69]
	v_mfma_f32_16x16x32_bf16 v[70:73], v[142:145], v[166:169], v[70:73]
	v_mfma_f32_16x16x32_bf16 v[74:77], v[134:137], v[174:177], v[74:77]
	v_mfma_f32_16x16x32_bf16 v[78:81], v[142:145], v[174:177], v[78:81]
	v_mfma_f32_16x16x32_bf16 v[86:89], v[134:137], v[182:185], v[86:89]
	v_mfma_f32_16x16x32_bf16 v[94:97], v[142:145], v[182:185], v[94:97]
	v_mfma_f32_16x16x32_bf16 v[102:105], v[134:137], v[192:195], v[102:105]
	v_mfma_f32_16x16x32_bf16 v[110:113], v[142:145], v[192:195], v[110:113]
	s_setprio 0
	s_setprio 1
	v_mfma_f32_16x16x32_bf16 v[82:85], v[146:149], v[162:165], v[82:85]
	v_mfma_f32_16x16x32_bf16 v[90:93], v[154:157], v[162:165], v[90:93]
	v_mfma_f32_16x16x32_bf16 v[98:101], v[146:149], v[170:173], v[98:101]
	v_mfma_f32_16x16x32_bf16 v[106:109], v[154:157], v[170:173], v[106:109]
	v_mfma_f32_16x16x32_bf16 v[114:117], v[146:149], v[178:181], v[114:117]
	v_mfma_f32_16x16x32_bf16 v[118:121], v[154:157], v[178:181], v[118:121]
	v_mfma_f32_16x16x32_bf16 v[122:125], v[146:149], v[188:191], v[122:125]
	v_mfma_f32_16x16x32_bf16 v[126:129], v[154:157], v[188:191], v[126:129]
	v_mfma_f32_16x16x32_bf16 v[82:85], v[150:153], v[166:169], v[82:85]
	v_mfma_f32_16x16x32_bf16 v[90:93], v[158:161], v[166:169], v[90:93]
	v_mfma_f32_16x16x32_bf16 v[98:101], v[150:153], v[174:177], v[98:101]
	v_mfma_f32_16x16x32_bf16 v[106:109], v[158:161], v[174:177], v[106:109]
	v_mfma_f32_16x16x32_bf16 v[114:117], v[150:153], v[182:185], v[114:117]
	v_mfma_f32_16x16x32_bf16 v[118:121], v[158:161], v[182:185], v[118:121]
	v_mfma_f32_16x16x32_bf16 v[122:125], v[150:153], v[192:195], v[122:125]
	v_mfma_f32_16x16x32_bf16 v[126:129], v[158:161], v[192:195], v[126:129]
	s_setprio 0
	s_barrier
	s_add_i32 s72, 0, 0x18000
	s_add_i32 s73, 0, 0x1c000
	v_add_u32_e32 v142, s72, v207
	v_add_u32_e32 v158, s73, v207
	ds_read_b128 v[130:133], v142
	ds_read_b128 v[134:137], v142 offset:1024
	ds_read_b128 v[138:141], v142 offset:2048
	ds_read_b128 v[142:145], v142 offset:3072
	ds_read_b128 v[146:149], v158
	ds_read_b128 v[150:153], v158 offset:1024
	ds_read_b128 v[154:157], v158 offset:2048
	ds_read_b128 v[158:161], v158 offset:3072
	s_add_u32 s54, s54, 0x160000
	s_addc_u32 s55, s55, 0
	ds_read_b128 v[162:165], v237 offset:32768
	ds_read_b128 v[166:169], v237 offset:33792
	ds_read_b128 v[170:173], v237 offset:34816
	ds_read_b128 v[174:177], v237 offset:35840
	ds_read_b128 v[178:181], v237 offset:36864
	ds_read_b128 v[182:185], v237 offset:37888
	ds_read_b128 v[188:191], v237 offset:38912
	ds_read_b128 v[192:195], v237 offset:39936
	s_mov_b32 m0, s60
	v_lshl_add_u64 v[196:197], s[54:55], 0, v[186:187]
	s_add_u32 s54, s54, 0xb0000
	s_addc_u32 s55, s55, 0
	global_load_lds_dwordx4 v[196:197], off
	s_mov_b32 m0, s61
	v_lshl_add_u64 v[196:197], s[54:55], 0, v[186:187]
	global_load_lds_dwordx4 v[196:197], off
	s_waitcnt vmcnt(8)
	s_waitcnt lgkmcnt(0)
	s_barrier
	s_setprio 1
	s_waitcnt lgkmcnt(0)
	v_mfma_f32_16x16x32_bf16 v[2:5], v[130:133], v[162:165], v[2:5]
	v_mfma_f32_16x16x32_bf16 v[6:9], v[138:141], v[162:165], v[6:9]
	v_mfma_f32_16x16x32_bf16 v[14:17], v[130:133], v[170:173], v[14:17]
	v_mfma_f32_16x16x32_bf16 v[22:25], v[138:141], v[170:173], v[22:25]
	v_mfma_f32_16x16x32_bf16 v[30:33], v[130:133], v[178:181], v[30:33]
	v_mfma_f32_16x16x32_bf16 v[38:41], v[138:141], v[178:181], v[38:41]
	v_mfma_f32_16x16x32_bf16 v[46:49], v[130:133], v[188:191], v[46:49]
	v_mfma_f32_16x16x32_bf16 v[54:57], v[138:141], v[188:191], v[54:57]
	v_mfma_f32_16x16x32_bf16 v[2:5], v[134:137], v[166:169], v[2:5]
	v_mfma_f32_16x16x32_bf16 v[6:9], v[142:145], v[166:169], v[6:9]
	v_mfma_f32_16x16x32_bf16 v[14:17], v[134:137], v[174:177], v[14:17]
	v_mfma_f32_16x16x32_bf16 v[22:25], v[142:145], v[174:177], v[22:25]
	v_mfma_f32_16x16x32_bf16 v[30:33], v[134:137], v[182:185], v[30:33]
	v_mfma_f32_16x16x32_bf16 v[38:41], v[142:145], v[182:185], v[38:41]
	v_mfma_f32_16x16x32_bf16 v[46:49], v[134:137], v[192:195], v[46:49]
	v_mfma_f32_16x16x32_bf16 v[54:57], v[142:145], v[192:195], v[54:57]
	s_setprio 0
	s_setprio 1
	v_mfma_f32_16x16x32_bf16 v[10:13], v[146:149], v[162:165], v[10:13]
	v_mfma_f32_16x16x32_bf16 v[18:21], v[154:157], v[162:165], v[18:21]
	v_mfma_f32_16x16x32_bf16 v[26:29], v[146:149], v[170:173], v[26:29]
	v_mfma_f32_16x16x32_bf16 v[34:37], v[154:157], v[170:173], v[34:37]
	v_mfma_f32_16x16x32_bf16 v[42:45], v[146:149], v[178:181], v[42:45]
	v_mfma_f32_16x16x32_bf16 v[50:53], v[154:157], v[178:181], v[50:53]
	v_mfma_f32_16x16x32_bf16 v[58:61], v[146:149], v[188:191], v[58:61]
	v_mfma_f32_16x16x32_bf16 v[62:65], v[154:157], v[188:191], v[62:65]
	v_mfma_f32_16x16x32_bf16 v[10:13], v[150:153], v[166:169], v[10:13]
	v_mfma_f32_16x16x32_bf16 v[18:21], v[158:161], v[166:169], v[18:21]
	v_mfma_f32_16x16x32_bf16 v[26:29], v[150:153], v[174:177], v[26:29]
	v_mfma_f32_16x16x32_bf16 v[34:37], v[158:161], v[174:177], v[34:37]
	v_mfma_f32_16x16x32_bf16 v[42:45], v[150:153], v[182:185], v[42:45]
	v_mfma_f32_16x16x32_bf16 v[50:53], v[158:161], v[182:185], v[50:53]
	v_mfma_f32_16x16x32_bf16 v[58:61], v[150:153], v[192:195], v[58:61]
	v_mfma_f32_16x16x32_bf16 v[62:65], v[158:161], v[192:195], v[62:65]
	s_setprio 0
	s_barrier
	s_add_u32 s54, s52, 0x80
	s_addc_u32 s55, s53, 0
	ds_read_b128 v[162:165], v237 offset:49152
	ds_read_b128 v[166:169], v237 offset:50176
	ds_read_b128 v[170:173], v237 offset:51200
	ds_read_b128 v[174:177], v237 offset:52224
	ds_read_b128 v[178:181], v237 offset:53248
	ds_read_b128 v[182:185], v237 offset:54272
	ds_read_b128 v[188:191], v237 offset:55296
	ds_read_b128 v[192:195], v237 offset:56320
	s_add_i32 s72, s72, s57
	v_lshl_add_u64 v[196:197], s[54:55], 0, v[202:203]
	s_mov_b32 m0, s72
	s_add_u32 s54, s54, 0xb0000
	global_load_lds_dwordx4 v[196:197], off
	s_addc_u32 s55, s55, 0
	s_add_i32 m0, s72, 0x2000
	s_add_u32 s52, s52, 0x160080
	s_addc_u32 s53, s53, 0
	v_lshl_add_u64 v[196:197], s[54:55], 0, v[202:203]
	global_load_lds_dwordx4 v[196:197], off
	s_add_i32 s54, s73, s57
	v_lshl_add_u64 v[196:197], s[52:53], 0, v[202:203]
	s_add_u32 s52, s52, 0xb0000
	s_mov_b32 m0, s54
	s_addc_u32 s53, s53, 0
	global_load_lds_dwordx4 v[196:197], off
	s_add_i32 m0, s54, 0x2000
	v_lshl_add_u64 v[196:197], s[52:53], 0, v[202:203]
	global_load_lds_dwordx4 v[196:197], off
	s_mov_b32 m0, s62
	v_lshl_add_u64 v[196:197], s[46:47], 0, v[186:187]
	s_add_u32 s46, s46, 0xb0000
	s_addc_u32 s47, s47, 0
	global_load_lds_dwordx4 v[196:197], off
	s_mov_b32 m0, s63
	v_lshl_add_u64 v[196:197], s[46:47], 0, v[186:187]
	global_load_lds_dwordx4 v[196:197], off
	s_waitcnt vmcnt(8)
	s_waitcnt lgkmcnt(0)
	s_barrier
	s_setprio 1
	s_waitcnt lgkmcnt(0)
	v_mfma_f32_16x16x32_bf16 v[66:69], v[130:133], v[162:165], v[66:69]
	v_mfma_f32_16x16x32_bf16 v[70:73], v[138:141], v[162:165], v[70:73]
	v_mfma_f32_16x16x32_bf16 v[74:77], v[130:133], v[170:173], v[74:77]
	v_mfma_f32_16x16x32_bf16 v[78:81], v[138:141], v[170:173], v[78:81]
	v_mfma_f32_16x16x32_bf16 v[86:89], v[130:133], v[178:181], v[86:89]
	v_mfma_f32_16x16x32_bf16 v[94:97], v[138:141], v[178:181], v[94:97]
	v_mfma_f32_16x16x32_bf16 v[102:105], v[130:133], v[188:191], v[102:105]
	v_mfma_f32_16x16x32_bf16 v[110:113], v[138:141], v[188:191], v[110:113]
	v_mfma_f32_16x16x32_bf16 v[66:69], v[134:137], v[166:169], v[66:69]
	v_mfma_f32_16x16x32_bf16 v[70:73], v[142:145], v[166:169], v[70:73]
	v_mfma_f32_16x16x32_bf16 v[74:77], v[134:137], v[174:177], v[74:77]
	v_mfma_f32_16x16x32_bf16 v[78:81], v[142:145], v[174:177], v[78:81]
	v_mfma_f32_16x16x32_bf16 v[86:89], v[134:137], v[182:185], v[86:89]
	v_mfma_f32_16x16x32_bf16 v[94:97], v[142:145], v[182:185], v[94:97]
	v_mfma_f32_16x16x32_bf16 v[102:105], v[134:137], v[192:195], v[102:105]
	v_mfma_f32_16x16x32_bf16 v[110:113], v[142:145], v[192:195], v[110:113]
	s_setprio 0
	s_setprio 1
	v_mfma_f32_16x16x32_bf16 v[82:85], v[146:149], v[162:165], v[82:85]
	v_mfma_f32_16x16x32_bf16 v[90:93], v[154:157], v[162:165], v[90:93]
	v_mfma_f32_16x16x32_bf16 v[98:101], v[146:149], v[170:173], v[98:101]
	v_mfma_f32_16x16x32_bf16 v[106:109], v[154:157], v[170:173], v[106:109]
	v_mfma_f32_16x16x32_bf16 v[114:117], v[146:149], v[178:181], v[114:117]
	v_mfma_f32_16x16x32_bf16 v[118:121], v[154:157], v[178:181], v[118:121]
	v_mfma_f32_16x16x32_bf16 v[122:125], v[146:149], v[188:191], v[122:125]
	v_mfma_f32_16x16x32_bf16 v[126:129], v[154:157], v[188:191], v[126:129]
	v_mfma_f32_16x16x32_bf16 v[82:85], v[150:153], v[166:169], v[82:85]
	v_mfma_f32_16x16x32_bf16 v[90:93], v[158:161], v[166:169], v[90:93]
	v_mfma_f32_16x16x32_bf16 v[98:101], v[150:153], v[174:177], v[98:101]
	v_mfma_f32_16x16x32_bf16 v[106:109], v[158:161], v[174:177], v[106:109]
	v_mfma_f32_16x16x32_bf16 v[114:117], v[150:153], v[182:185], v[114:117]
	v_mfma_f32_16x16x32_bf16 v[118:121], v[158:161], v[182:185], v[118:121]
	v_mfma_f32_16x16x32_bf16 v[122:125], v[150:153], v[192:195], v[122:125]
	v_mfma_f32_16x16x32_bf16 v[126:129], v[158:161], v[192:195], v[126:129]
	s_setprio 0
	s_barrier
	s_add_i32 s71, s71, 2
	s_add_u32 s9, s9, 0x100
	s_addc_u32 s27, s27, 0
	s_add_u32 s28, s28, 0x100
	s_addc_u32 s29, s29, 0
	s_add_u32 s44, s44, 0x100
	s_addc_u32 s45, s45, 0
	s_cmpk_gt_u32 s71, 0x55
	s_cbranch_scc0 .LBB0_1286
	s_and_b64 vcc, exec, s[18:19]
	s_cbranch_vccz .LBB0_1289
	s_barrier
.LBB0_1289:
	v_lshl_add_u32 v188, s8, 8, v205
	v_or_b32_e32 v194, 16, v188
	v_or_b32_e32 v192, 32, v188
	v_or_b32_e32 v190, 48, v188
	s_and_b64 vcc, exec, s[20:21]
	v_ashrrev_i32_e32 v189, 31, v188
	v_ashrrev_i32_e32 v195, 31, v194
	v_ashrrev_i32_e32 v193, 31, v192
	v_ashrrev_i32_e32 v191, 31, v190
	s_cbranch_vccz .LBB0_1377
	v_lshlrev_b32_e32 v250, 5, v205
	v_add_u32_e32 v250, 0x24f80, v250
	ds_read_b128 v[238:241], v250 offset:16
	ds_read_b128 v[242:245], v250
	ds_read_b128 v[178:181], v250 offset:528
	ds_read_b128 v[182:185], v250 offset:512
	ds_read_b128 v[170:173], v250 offset:1040
	ds_read_b128 v[174:177], v250 offset:1024
	v_add_u32_e32 v208, 0x80, v188
	v_ashrrev_i32_e32 v209, 31, v208
	ds_read_b128 v[162:165], v250 offset:1552
	ds_read_b128 v[166:169], v250 offset:1536
	v_add_u32_e32 v200, 0x90, v188
	v_ashrrev_i32_e32 v201, 31, v200
	ds_read_b128 v[154:157], v250 offset:4112
	ds_read_b128 v[158:161], v250 offset:4096
	v_add_u32_e32 v198, 0xa0, v188
	v_ashrrev_i32_e32 v199, 31, v198
	ds_read_b128 v[146:149], v250 offset:4624
	ds_read_b128 v[150:153], v250 offset:4608
	v_add_u32_e32 v196, 0xb0, v188
	v_ashrrev_i32_e32 v197, 31, v196
	ds_read_b128 v[138:141], v250 offset:5136
	ds_read_b128 v[142:145], v250 offset:5120
	ds_read_b128 v[130:133], v250 offset:5648
	ds_read_b128 v[134:137], v250 offset:5632
	s_cmp_eq_u32 s26, 0
	s_cselect_b64 s[28:29], -1, 0
	s_and_b64 s[44:45], s[40:41], s[28:29]
	s_waitcnt lgkmcnt(0)
	v_max_f32_e32 v241, v241, v241
	v_max_f32_e32 v240, v240, v240
	v_max_f32_e32 v243, v243, v243
	v_max_f32_e32 v242, v242, v242
	v_max_f32_e32 v245, v245, v245
	v_max_f32_e32 v244, v244, v244
	v_max_f32_e32 v240, v240, v241
	v_max_f32_e32 v242, v242, v243
	v_max_f32_e32 v243, v244, v245
	v_max3_f32 v238, v238, v239, v240
	v_max3_f32 v238, v242, v243, v238
	v_fmamk_f32 v238, v238, 0x3c077551, v231
	s_and_saveexec_b64 s[46:47], s[44:45]
	s_cbranch_execz .LBB0_1292
	v_lshl_add_u64 v[240:241], v[188:189], 2, s[16:17]
	global_store_dword v[240:241], v238, off
